# prompt-scan o stores: SGPR base advanced per store + 32-bit lane offset instead of 64-bit VALU address arithmetic
# baseline (speedup 1.0000x reference)
; __device__ __forceinline__ void scan_unit(const Ctx& C0, const float* scn, int T, int quarter, const float* S0, float* Sout, unsigned char* obase, int mode) {
;     ...
;         for (int k = 0; k < nch; ++k) {
;             const unsigned aq = (unsigned)(size_t)(C.lds + (k & 1) * SLOT_B) + 16u * (unsigned)q, av = (unsigned)(size_t)(C.lds + (k & 1) * SLOT_B) + (320u + (unsigned)irow) * 4u;
;             float osel0, osel1;
;             asm volatile(SCAN_CHUNK_ASM : "+v"(S0x), "+v"(S1x), "+v"(S2x), "+v"(S3x), "=&v"(osel0), "=&v"(osel1) : "v"(aq), "v"(av), "v"(q) : SCAN_CHUNK_CLOBBERS, "memory");
;             if (mode == 0) { *(float*)(obase + (size_t)(k * 32 + q) * UPITCH_B + rl * 4) = osel0; *(float*)(obase + (size_t)(k * 32 + 16 + q) * UPITCH_B + rl * 4) = osel1; }
.LBB0_683:
	s_and_b64 vcc, exec, s[0:1]
	s_cbranch_vccz .LBB0_687
	v_lshrrev_b32_e32 v2, 4, v53
	s_lshl_b32 s1, s9, 2
	s_bfe_u32 s0, s72, 0x20003
	v_and_or_b32 v0, s1, 12, v2
	v_lshl_or_b32 v0, s0, 4, v0
	s_lshl_b32 s10, s2, 8
	s_lshl_b32 s0, s0, 6
	s_mul_i32 s9, s3, 0x5600000
	v_mov_b32_e32 v5, 0x500
	s_or_b32 s0, s10, s0
	s_mul_hi_i32 s1, s3, 0x5600000
	v_lshl_or_b32 v6, v0, 2, v5
	s_add_i32 s11, 0, 0xc000
	s_or_b32 s0, s9, s0
	s_waitcnt lgkmcnt(0)
	v_and_b32_e32 v3, 15, v52
	v_add_u32_e32 v9, 0, v6
	v_add_u32_e32 v11, s11, v6
	v_mov_b32_e32 v6, s0
	v_mov_b32_e32 v7, s1
	s_movk_i32 s0, 0x2b00
	v_mad_u64_u32 v[6:7], s[0:1], v3, s0, v[6:7]
	s_lshr_b32 s0, s8, 2
	s_and_b32 s0, s0, 48
	v_lshlrev_b32_e32 v2, 2, v2
	s_barrier
	v_or3_b32 v6, s0, v2, v6
	v_readlane_b32 s0, v253, 4
	v_lshlrev_b32_e32 v4, 4, v3
	v_readlane_b32 s1, v253, 5
	v_add_u32_e32 v5, 0, v4
	v_add_u32_e32 v10, s11, v4
	s_nop 1
	s_add_u32 s98, s0, 0xfc29300
	s_addc_u32 s99, s1, 0
	v_mov_b32_e32 v8, 0
	s_mov_b64 s[0:1], 0
	v_mov_b32_e32 v12, 0
	v_mov_b32_e32 v13, 0
	v_mov_b32_e32 v2, 0
	v_mov_b32_e32 v138, v2
	v_mov_b32_e32 v139, v13
	v_mov_b32_e32 v140, v12
	v_mov_b32_e32 v141, v8
.LBB0_685:
	ds_read_b128 v[164:167], v5 offset:0
	ds_read_b128 v[168:171], v5 offset:256
	ds_read_b128 v[172:175], v5 offset:512
	ds_read_b128 v[176:179], v5 offset:768
	ds_read_b128 v[180:183], v5 offset:1024
	ds_read_b32 v184, v9 offset:0
	ds_read_b128 v[186:189], v5 offset:1536
	ds_read_b128 v[190:193], v5 offset:1792
	ds_read_b128 v[194:197], v5 offset:2048
	ds_read_b128 v[198:201], v5 offset:2304
	ds_read_b128 v[202:205], v5 offset:2560
	ds_read_b32 v206, v9 offset:1536
	ds_read_b128 v[208:211], v5 offset:3072
	s_waitcnt lgkmcnt(12)
	v_pk_mul_f32 v[144:145], v[138:139], v[164:165]
	v_pk_fma_f32 v[144:145], v[140:141], v[166:167], v[144:145]
	v_add_f32 v146, v144, v145
	ds_read_b128 v[212:215], v5 offset:3328
	ds_read_b128 v[216:219], v5 offset:3584
	ds_read_b128 v[220:223], v5 offset:3840
	ds_read_b128 v[224:227], v5 offset:4096
	ds_read_b32 v228, v9 offset:3072
	ds_read_b128 v[230:233], v5 offset:4608
	v_add_f32_dpp v146, v146, v146 quad_perm:[1,0,3,2] row_mask:0xf bank_mask:0xf bound_ctrl:1
	s_nop 0
	s_nop 0
	v_add_f32_dpp v146, v146, v146 quad_perm:[2,3,0,1] row_mask:0xf bank_mask:0xf bound_ctrl:1
	s_waitcnt lgkmcnt(12)
	v_pk_mul_f32 v[176:177], v[176:177], v[184:185] op_sel_hi:[1,0]
	v_add_f32_dpp v146, v146, v146 row_half_mirror row_mask:0xf bank_mask:0xf bound_ctrl:1
	v_pk_mul_f32 v[178:179], v[178:179], v[184:185] op_sel_hi:[1,0]
	s_nop 0
	v_add_f32_dpp v146, v146, v146 row_mirror row_mask:0xf bank_mask:0xf bound_ctrl:1
	v_pk_fma_f32 v[176:177], v[146:147], v[168:169], v[176:177] op_sel_hi:[0,1,1] neg_lo:[1,0,0] neg_hi:[1,0,0]
	v_pk_fma_f32 v[178:179], v[146:147], v[170:171], v[178:179] op_sel_hi:[0,1,1] neg_lo:[1,0,0] neg_hi:[1,0,0]
	v_pk_fma_f32 v[138:139], v[138:139], v[172:173], v[176:177]
	v_pk_fma_f32 v[140:141], v[140:141], v[174:175], v[178:179]
	v_pk_mul_f32 v[144:145], v[138:139], v[186:187]
	v_pk_fma_f32 v[144:145], v[140:141], v[188:189], v[144:145]
	v_add_f32 v146, v144, v145
	ds_read_b128 v[234:237], v5 offset:4864
	ds_read_b128 v[238:241], v5 offset:5120
	ds_read_b128 v[242:245], v5 offset:5376
	ds_read_b128 v[246:249], v5 offset:5632
	ds_read_b32 v250, v9 offset:4608
	ds_read_b128 v[164:167], v5 offset:6144
	v_add_f32_dpp v146, v146, v146 quad_perm:[1,0,3,2] row_mask:0xf bank_mask:0xf bound_ctrl:1
	v_pk_mul_f32 v[180:181], v[138:139], v[180:181]
	v_pk_fma_f32 v[180:181], v[140:141], v[182:183], v[180:181]
	v_add_f32_dpp v146, v146, v146 quad_perm:[2,3,0,1] row_mask:0xf bank_mask:0xf bound_ctrl:1
	s_waitcnt lgkmcnt(12)
	v_pk_mul_f32 v[198:199], v[198:199], v[206:207] op_sel_hi:[1,0]
	v_add_f32_dpp v146, v146, v146 row_half_mirror row_mask:0xf bank_mask:0xf bound_ctrl:1
	v_pk_mul_f32 v[200:201], v[200:201], v[206:207] op_sel_hi:[1,0]
	v_add_f32 v148, v180, v181
	v_add_f32_dpp v146, v146, v146 row_mirror row_mask:0xf bank_mask:0xf bound_ctrl:1
	v_pk_fma_f32 v[198:199], v[146:147], v[190:191], v[198:199] op_sel_hi:[0,1,1] neg_lo:[1,0,0] neg_hi:[1,0,0]
	v_pk_fma_f32 v[200:201], v[146:147], v[192:193], v[200:201] op_sel_hi:[0,1,1] neg_lo:[1,0,0] neg_hi:[1,0,0]
	v_pk_fma_f32 v[138:139], v[138:139], v[194:195], v[198:199]
	v_pk_fma_f32 v[140:141], v[140:141], v[196:197], v[200:201]
	v_pk_mul_f32 v[144:145], v[138:139], v[208:209]
	v_pk_fma_f32 v[144:145], v[140:141], v[210:211], v[144:145]
	v_add_f32 v146, v144, v145
	ds_read_b128 v[168:171], v5 offset:6400
	ds_read_b128 v[172:175], v5 offset:6656
	ds_read_b128 v[176:179], v5 offset:6912
	ds_read_b128 v[180:183], v5 offset:7168
	ds_read_b32 v184, v9 offset:6144
	ds_read_b128 v[186:189], v5 offset:7680
	v_add_f32_dpp v146, v146, v146 quad_perm:[1,0,3,2] row_mask:0xf bank_mask:0xf bound_ctrl:1
	v_pk_mul_f32 v[202:203], v[138:139], v[202:203]
	v_pk_fma_f32 v[202:203], v[140:141], v[204:205], v[202:203]
	v_add_f32_dpp v146, v146, v146 quad_perm:[2,3,0,1] row_mask:0xf bank_mask:0xf bound_ctrl:1
	s_waitcnt lgkmcnt(12)
	v_pk_mul_f32 v[220:221], v[220:221], v[228:229] op_sel_hi:[1,0]
	v_add_f32_dpp v146, v146, v146 row_half_mirror row_mask:0xf bank_mask:0xf bound_ctrl:1
	v_pk_mul_f32 v[222:223], v[222:223], v[228:229] op_sel_hi:[1,0]
	v_add_f32 v149, v202, v203
	v_add_f32_dpp v146, v146, v146 row_mirror row_mask:0xf bank_mask:0xf bound_ctrl:1
	v_pk_fma_f32 v[220:221], v[146:147], v[212:213], v[220:221] op_sel_hi:[0,1,1] neg_lo:[1,0,0] neg_hi:[1,0,0]
	v_pk_fma_f32 v[222:223], v[146:147], v[214:215], v[222:223] op_sel_hi:[0,1,1] neg_lo:[1,0,0] neg_hi:[1,0,0]
	v_pk_fma_f32 v[138:139], v[138:139], v[216:217], v[220:221]
	v_pk_fma_f32 v[140:141], v[140:141], v[218:219], v[222:223]
	v_pk_mul_f32 v[144:145], v[138:139], v[230:231]
	v_pk_fma_f32 v[144:145], v[140:141], v[232:233], v[144:145]
	v_add_f32 v146, v144, v145
	ds_read_b128 v[190:193], v5 offset:7936
	ds_read_b128 v[194:197], v5 offset:8192
	ds_read_b128 v[198:201], v5 offset:8448
	ds_read_b128 v[202:205], v5 offset:8704
	ds_read_b32 v206, v9 offset:7680
	ds_read_b128 v[208:211], v5 offset:9216
	v_add_f32_dpp v146, v146, v146 quad_perm:[1,0,3,2] row_mask:0xf bank_mask:0xf bound_ctrl:1
	v_pk_mul_f32 v[224:225], v[138:139], v[224:225]
	v_pk_fma_f32 v[224:225], v[140:141], v[226:227], v[224:225]
	v_add_f32_dpp v146, v146, v146 quad_perm:[2,3,0,1] row_mask:0xf bank_mask:0xf bound_ctrl:1
	s_waitcnt lgkmcnt(12)
	v_pk_mul_f32 v[242:243], v[242:243], v[250:251] op_sel_hi:[1,0]
	v_add_f32_dpp v146, v146, v146 row_half_mirror row_mask:0xf bank_mask:0xf bound_ctrl:1
	v_pk_mul_f32 v[244:245], v[244:245], v[250:251] op_sel_hi:[1,0]
	v_add_f32 v150, v224, v225
	v_add_f32_dpp v146, v146, v146 row_mirror row_mask:0xf bank_mask:0xf bound_ctrl:1
	v_pk_fma_f32 v[242:243], v[146:147], v[234:235], v[242:243] op_sel_hi:[0,1,1] neg_lo:[1,0,0] neg_hi:[1,0,0]
	v_pk_fma_f32 v[244:245], v[146:147], v[236:237], v[244:245] op_sel_hi:[0,1,1] neg_lo:[1,0,0] neg_hi:[1,0,0]
	v_pk_fma_f32 v[138:139], v[138:139], v[238:239], v[242:243]
	v_pk_fma_f32 v[140:141], v[140:141], v[240:241], v[244:245]
	v_pk_mul_f32 v[144:145], v[138:139], v[164:165]
	v_pk_fma_f32 v[144:145], v[140:141], v[166:167], v[144:145]
	v_add_f32 v146, v144, v145
	ds_read_b128 v[212:215], v5 offset:9472
	ds_read_b128 v[216:219], v5 offset:9728
	ds_read_b128 v[220:223], v5 offset:9984
	ds_read_b128 v[224:227], v5 offset:10240
	ds_read_b32 v228, v9 offset:9216
	ds_read_b128 v[230:233], v5 offset:10752
	v_add_f32_dpp v146, v146, v146 quad_perm:[1,0,3,2] row_mask:0xf bank_mask:0xf bound_ctrl:1
	v_pk_mul_f32 v[246:247], v[138:139], v[246:247]
	v_pk_fma_f32 v[246:247], v[140:141], v[248:249], v[246:247]
	v_add_f32_dpp v146, v146, v146 quad_perm:[2,3,0,1] row_mask:0xf bank_mask:0xf bound_ctrl:1
	s_waitcnt lgkmcnt(12)
	v_pk_mul_f32 v[176:177], v[176:177], v[184:185] op_sel_hi:[1,0]
	v_add_f32_dpp v146, v146, v146 row_half_mirror row_mask:0xf bank_mask:0xf bound_ctrl:1
	v_pk_mul_f32 v[178:179], v[178:179], v[184:185] op_sel_hi:[1,0]
	v_add_f32 v151, v246, v247
	v_add_f32_dpp v146, v146, v146 row_mirror row_mask:0xf bank_mask:0xf bound_ctrl:1
	v_pk_fma_f32 v[176:177], v[146:147], v[168:169], v[176:177] op_sel_hi:[0,1,1] neg_lo:[1,0,0] neg_hi:[1,0,0]
	v_pk_fma_f32 v[178:179], v[146:147], v[170:171], v[178:179] op_sel_hi:[0,1,1] neg_lo:[1,0,0] neg_hi:[1,0,0]
	v_pk_fma_f32 v[138:139], v[138:139], v[172:173], v[176:177]
	v_pk_fma_f32 v[140:141], v[140:141], v[174:175], v[178:179]
	v_pk_mul_f32 v[144:145], v[138:139], v[186:187]
	v_pk_fma_f32 v[144:145], v[140:141], v[188:189], v[144:145]
	v_add_f32 v146, v144, v145
	ds_read_b128 v[234:237], v5 offset:11008
	ds_read_b128 v[238:241], v5 offset:11264
	ds_read_b128 v[242:245], v5 offset:11520
	ds_read_b128 v[246:249], v5 offset:11776
	ds_read_b32 v250, v9 offset:10752
	ds_read_b128 v[164:167], v5 offset:12288
	v_add_f32_dpp v146, v146, v146 quad_perm:[1,0,3,2] row_mask:0xf bank_mask:0xf bound_ctrl:1
	v_pk_mul_f32 v[180:181], v[138:139], v[180:181]
	v_pk_fma_f32 v[180:181], v[140:141], v[182:183], v[180:181]
	v_add_f32_dpp v146, v146, v146 quad_perm:[2,3,0,1] row_mask:0xf bank_mask:0xf bound_ctrl:1
	s_waitcnt lgkmcnt(12)
	v_pk_mul_f32 v[198:199], v[198:199], v[206:207] op_sel_hi:[1,0]
	v_add_f32_dpp v146, v146, v146 row_half_mirror row_mask:0xf bank_mask:0xf bound_ctrl:1
	v_pk_mul_f32 v[200:201], v[200:201], v[206:207] op_sel_hi:[1,0]
	v_add_f32 v152, v180, v181
	v_add_f32_dpp v146, v146, v146 row_mirror row_mask:0xf bank_mask:0xf bound_ctrl:1
	v_pk_fma_f32 v[198:199], v[146:147], v[190:191], v[198:199] op_sel_hi:[0,1,1] neg_lo:[1,0,0] neg_hi:[1,0,0]
	v_pk_fma_f32 v[200:201], v[146:147], v[192:193], v[200:201] op_sel_hi:[0,1,1] neg_lo:[1,0,0] neg_hi:[1,0,0]
	v_pk_fma_f32 v[138:139], v[138:139], v[194:195], v[198:199]
	v_pk_fma_f32 v[140:141], v[140:141], v[196:197], v[200:201]
	v_pk_mul_f32 v[144:145], v[138:139], v[208:209]
	v_pk_fma_f32 v[144:145], v[140:141], v[210:211], v[144:145]
	v_add_f32 v146, v144, v145
	ds_read_b128 v[168:171], v5 offset:12544
	ds_read_b128 v[172:175], v5 offset:12800
	ds_read_b128 v[176:179], v5 offset:13056
	ds_read_b128 v[180:183], v5 offset:13312
	ds_read_b32 v184, v9 offset:12288
	ds_read_b128 v[186:189], v5 offset:13824
	v_add_f32_dpp v146, v146, v146 quad_perm:[1,0,3,2] row_mask:0xf bank_mask:0xf bound_ctrl:1
	v_pk_mul_f32 v[202:203], v[138:139], v[202:203]
	v_pk_fma_f32 v[202:203], v[140:141], v[204:205], v[202:203]
	v_add_f32_dpp v146, v146, v146 quad_perm:[2,3,0,1] row_mask:0xf bank_mask:0xf bound_ctrl:1
	s_waitcnt lgkmcnt(12)
	v_pk_mul_f32 v[220:221], v[220:221], v[228:229] op_sel_hi:[1,0]
	v_add_f32_dpp v146, v146, v146 row_half_mirror row_mask:0xf bank_mask:0xf bound_ctrl:1
	v_pk_mul_f32 v[222:223], v[222:223], v[228:229] op_sel_hi:[1,0]
	v_add_f32 v153, v202, v203
	v_add_f32_dpp v146, v146, v146 row_mirror row_mask:0xf bank_mask:0xf bound_ctrl:1
	v_pk_fma_f32 v[220:221], v[146:147], v[212:213], v[220:221] op_sel_hi:[0,1,1] neg_lo:[1,0,0] neg_hi:[1,0,0]
	v_pk_fma_f32 v[222:223], v[146:147], v[214:215], v[222:223] op_sel_hi:[0,1,1] neg_lo:[1,0,0] neg_hi:[1,0,0]
	v_pk_fma_f32 v[138:139], v[138:139], v[216:217], v[220:221]
	v_pk_fma_f32 v[140:141], v[140:141], v[218:219], v[222:223]
	v_pk_mul_f32 v[144:145], v[138:139], v[230:231]
	v_pk_fma_f32 v[144:145], v[140:141], v[232:233], v[144:145]
	v_add_f32 v146, v144, v145
	ds_read_b128 v[190:193], v5 offset:14080
	ds_read_b128 v[194:197], v5 offset:14336
	ds_read_b128 v[198:201], v5 offset:14592
	ds_read_b128 v[202:205], v5 offset:14848
	ds_read_b32 v206, v9 offset:13824
	ds_read_b128 v[208:211], v5 offset:15360
	v_add_f32_dpp v146, v146, v146 quad_perm:[1,0,3,2] row_mask:0xf bank_mask:0xf bound_ctrl:1
	v_pk_mul_f32 v[224:225], v[138:139], v[224:225]
	v_pk_fma_f32 v[224:225], v[140:141], v[226:227], v[224:225]
	v_add_f32_dpp v146, v146, v146 quad_perm:[2,3,0,1] row_mask:0xf bank_mask:0xf bound_ctrl:1
	s_waitcnt lgkmcnt(12)
	v_pk_mul_f32 v[242:243], v[242:243], v[250:251] op_sel_hi:[1,0]
	v_add_f32_dpp v146, v146, v146 row_half_mirror row_mask:0xf bank_mask:0xf bound_ctrl:1
	v_pk_mul_f32 v[244:245], v[244:245], v[250:251] op_sel_hi:[1,0]
	v_add_f32 v154, v224, v225
	v_add_f32_dpp v146, v146, v146 row_mirror row_mask:0xf bank_mask:0xf bound_ctrl:1
	v_pk_fma_f32 v[242:243], v[146:147], v[234:235], v[242:243] op_sel_hi:[0,1,1] neg_lo:[1,0,0] neg_hi:[1,0,0]
	v_pk_fma_f32 v[244:245], v[146:147], v[236:237], v[244:245] op_sel_hi:[0,1,1] neg_lo:[1,0,0] neg_hi:[1,0,0]
	v_pk_fma_f32 v[138:139], v[138:139], v[238:239], v[242:243]
	v_pk_fma_f32 v[140:141], v[140:141], v[240:241], v[244:245]
	v_pk_mul_f32 v[144:145], v[138:139], v[164:165]
	v_pk_fma_f32 v[144:145], v[140:141], v[166:167], v[144:145]
	v_add_f32 v146, v144, v145
	ds_read_b128 v[212:215], v5 offset:15616
	ds_read_b128 v[216:219], v5 offset:15872
	ds_read_b128 v[220:223], v5 offset:16128
	ds_read_b128 v[224:227], v5 offset:16384
	ds_read_b32 v228, v9 offset:15360
	ds_read_b128 v[230:233], v5 offset:16896
	v_add_f32_dpp v146, v146, v146 quad_perm:[1,0,3,2] row_mask:0xf bank_mask:0xf bound_ctrl:1
	v_pk_mul_f32 v[246:247], v[138:139], v[246:247]
	v_pk_fma_f32 v[246:247], v[140:141], v[248:249], v[246:247]
	v_add_f32_dpp v146, v146, v146 quad_perm:[2,3,0,1] row_mask:0xf bank_mask:0xf bound_ctrl:1
	s_waitcnt lgkmcnt(12)
	v_pk_mul_f32 v[176:177], v[176:177], v[184:185] op_sel_hi:[1,0]
	v_add_f32_dpp v146, v146, v146 row_half_mirror row_mask:0xf bank_mask:0xf bound_ctrl:1
	v_pk_mul_f32 v[178:179], v[178:179], v[184:185] op_sel_hi:[1,0]
	v_add_f32 v155, v246, v247
	v_add_f32_dpp v146, v146, v146 row_mirror row_mask:0xf bank_mask:0xf bound_ctrl:1
	v_pk_fma_f32 v[176:177], v[146:147], v[168:169], v[176:177] op_sel_hi:[0,1,1] neg_lo:[1,0,0] neg_hi:[1,0,0]
	v_pk_fma_f32 v[178:179], v[146:147], v[170:171], v[178:179] op_sel_hi:[0,1,1] neg_lo:[1,0,0] neg_hi:[1,0,0]
	v_pk_fma_f32 v[138:139], v[138:139], v[172:173], v[176:177]
	v_pk_fma_f32 v[140:141], v[140:141], v[174:175], v[178:179]
	v_pk_mul_f32 v[144:145], v[138:139], v[186:187]
	v_pk_fma_f32 v[144:145], v[140:141], v[188:189], v[144:145]
	v_add_f32 v146, v144, v145
	ds_read_b128 v[234:237], v5 offset:17152
	ds_read_b128 v[238:241], v5 offset:17408
	ds_read_b128 v[242:245], v5 offset:17664
	ds_read_b128 v[246:249], v5 offset:17920
	ds_read_b32 v250, v9 offset:16896
	ds_read_b128 v[164:167], v5 offset:18432
	v_add_f32_dpp v146, v146, v146 quad_perm:[1,0,3,2] row_mask:0xf bank_mask:0xf bound_ctrl:1
	v_pk_mul_f32 v[180:181], v[138:139], v[180:181]
	v_pk_fma_f32 v[180:181], v[140:141], v[182:183], v[180:181]
	v_add_f32_dpp v146, v146, v146 quad_perm:[2,3,0,1] row_mask:0xf bank_mask:0xf bound_ctrl:1
	s_waitcnt lgkmcnt(12)
	v_pk_mul_f32 v[198:199], v[198:199], v[206:207] op_sel_hi:[1,0]
	v_add_f32_dpp v146, v146, v146 row_half_mirror row_mask:0xf bank_mask:0xf bound_ctrl:1
	v_pk_mul_f32 v[200:201], v[200:201], v[206:207] op_sel_hi:[1,0]
	v_add_f32 v156, v180, v181
	v_add_f32_dpp v146, v146, v146 row_mirror row_mask:0xf bank_mask:0xf bound_ctrl:1
	v_pk_fma_f32 v[198:199], v[146:147], v[190:191], v[198:199] op_sel_hi:[0,1,1] neg_lo:[1,0,0] neg_hi:[1,0,0]
	v_pk_fma_f32 v[200:201], v[146:147], v[192:193], v[200:201] op_sel_hi:[0,1,1] neg_lo:[1,0,0] neg_hi:[1,0,0]
	v_pk_fma_f32 v[138:139], v[138:139], v[194:195], v[198:199]
	v_pk_fma_f32 v[140:141], v[140:141], v[196:197], v[200:201]
	v_pk_mul_f32 v[144:145], v[138:139], v[208:209]
	v_pk_fma_f32 v[144:145], v[140:141], v[210:211], v[144:145]
	v_add_f32 v146, v144, v145
	ds_read_b128 v[168:171], v5 offset:18688
	ds_read_b128 v[172:175], v5 offset:18944
	ds_read_b128 v[176:179], v5 offset:19200
	ds_read_b128 v[180:183], v5 offset:19456
	ds_read_b32 v184, v9 offset:18432
	ds_read_b128 v[186:189], v5 offset:19968
	v_add_f32_dpp v146, v146, v146 quad_perm:[1,0,3,2] row_mask:0xf bank_mask:0xf bound_ctrl:1
	v_pk_mul_f32 v[202:203], v[138:139], v[202:203]
	v_pk_fma_f32 v[202:203], v[140:141], v[204:205], v[202:203]
	v_add_f32_dpp v146, v146, v146 quad_perm:[2,3,0,1] row_mask:0xf bank_mask:0xf bound_ctrl:1
	s_waitcnt lgkmcnt(12)
	v_pk_mul_f32 v[220:221], v[220:221], v[228:229] op_sel_hi:[1,0]
	v_add_f32_dpp v146, v146, v146 row_half_mirror row_mask:0xf bank_mask:0xf bound_ctrl:1
	v_pk_mul_f32 v[222:223], v[222:223], v[228:229] op_sel_hi:[1,0]
	v_add_f32 v157, v202, v203
	v_add_f32_dpp v146, v146, v146 row_mirror row_mask:0xf bank_mask:0xf bound_ctrl:1
	v_pk_fma_f32 v[220:221], v[146:147], v[212:213], v[220:221] op_sel_hi:[0,1,1] neg_lo:[1,0,0] neg_hi:[1,0,0]
	v_pk_fma_f32 v[222:223], v[146:147], v[214:215], v[222:223] op_sel_hi:[0,1,1] neg_lo:[1,0,0] neg_hi:[1,0,0]
	v_pk_fma_f32 v[138:139], v[138:139], v[216:217], v[220:221]
	v_pk_fma_f32 v[140:141], v[140:141], v[218:219], v[222:223]
	v_pk_mul_f32 v[144:145], v[138:139], v[230:231]
	v_pk_fma_f32 v[144:145], v[140:141], v[232:233], v[144:145]
	v_add_f32 v146, v144, v145
	ds_read_b128 v[190:193], v5 offset:20224
	ds_read_b128 v[194:197], v5 offset:20480
	ds_read_b128 v[198:201], v5 offset:20736
	ds_read_b128 v[202:205], v5 offset:20992
	ds_read_b32 v206, v9 offset:19968
	ds_read_b128 v[208:211], v5 offset:21504
	v_add_f32_dpp v146, v146, v146 quad_perm:[1,0,3,2] row_mask:0xf bank_mask:0xf bound_ctrl:1
	v_pk_mul_f32 v[224:225], v[138:139], v[224:225]
	v_pk_fma_f32 v[224:225], v[140:141], v[226:227], v[224:225]
	v_add_f32_dpp v146, v146, v146 quad_perm:[2,3,0,1] row_mask:0xf bank_mask:0xf bound_ctrl:1
	s_waitcnt lgkmcnt(12)
	v_pk_mul_f32 v[242:243], v[242:243], v[250:251] op_sel_hi:[1,0]
	v_add_f32_dpp v146, v146, v146 row_half_mirror row_mask:0xf bank_mask:0xf bound_ctrl:1
	v_pk_mul_f32 v[244:245], v[244:245], v[250:251] op_sel_hi:[1,0]
	v_add_f32 v158, v224, v225
	v_add_f32_dpp v146, v146, v146 row_mirror row_mask:0xf bank_mask:0xf bound_ctrl:1
	v_pk_fma_f32 v[242:243], v[146:147], v[234:235], v[242:243] op_sel_hi:[0,1,1] neg_lo:[1,0,0] neg_hi:[1,0,0]
	v_pk_fma_f32 v[244:245], v[146:147], v[236:237], v[244:245] op_sel_hi:[0,1,1] neg_lo:[1,0,0] neg_hi:[1,0,0]
	v_pk_fma_f32 v[138:139], v[138:139], v[238:239], v[242:243]
	v_pk_fma_f32 v[140:141], v[140:141], v[240:241], v[244:245]
	v_pk_mul_f32 v[144:145], v[138:139], v[164:165]
	v_pk_fma_f32 v[144:145], v[140:141], v[166:167], v[144:145]
	v_add_f32 v146, v144, v145
	ds_read_b128 v[212:215], v5 offset:21760
	ds_read_b128 v[216:219], v5 offset:22016
	ds_read_b128 v[220:223], v5 offset:22272
	ds_read_b128 v[224:227], v5 offset:22528
	ds_read_b32 v228, v9 offset:21504
	ds_read_b128 v[230:233], v5 offset:23040
	v_add_f32_dpp v146, v146, v146 quad_perm:[1,0,3,2] row_mask:0xf bank_mask:0xf bound_ctrl:1
	v_pk_mul_f32 v[246:247], v[138:139], v[246:247]
	v_pk_fma_f32 v[246:247], v[140:141], v[248:249], v[246:247]
	v_add_f32_dpp v146, v146, v146 quad_perm:[2,3,0,1] row_mask:0xf bank_mask:0xf bound_ctrl:1
	s_waitcnt lgkmcnt(12)
	v_pk_mul_f32 v[176:177], v[176:177], v[184:185] op_sel_hi:[1,0]
	v_add_f32_dpp v146, v146, v146 row_half_mirror row_mask:0xf bank_mask:0xf bound_ctrl:1
	v_pk_mul_f32 v[178:179], v[178:179], v[184:185] op_sel_hi:[1,0]
	v_add_f32 v159, v246, v247
	v_add_f32_dpp v146, v146, v146 row_mirror row_mask:0xf bank_mask:0xf bound_ctrl:1
	v_pk_fma_f32 v[176:177], v[146:147], v[168:169], v[176:177] op_sel_hi:[0,1,1] neg_lo:[1,0,0] neg_hi:[1,0,0]
	v_pk_fma_f32 v[178:179], v[146:147], v[170:171], v[178:179] op_sel_hi:[0,1,1] neg_lo:[1,0,0] neg_hi:[1,0,0]
	v_pk_fma_f32 v[138:139], v[138:139], v[172:173], v[176:177]
	v_pk_fma_f32 v[140:141], v[140:141], v[174:175], v[178:179]
	v_pk_mul_f32 v[144:145], v[138:139], v[186:187]
	v_pk_fma_f32 v[144:145], v[140:141], v[188:189], v[144:145]
	v_add_f32 v146, v144, v145
	ds_read_b128 v[234:237], v5 offset:23296
	ds_read_b128 v[238:241], v5 offset:23552
	ds_read_b128 v[242:245], v5 offset:23808
	ds_read_b128 v[246:249], v5 offset:24064
	ds_read_b32 v250, v9 offset:23040
	ds_read_b128 v[164:167], v5 offset:24576
	v_add_f32_dpp v146, v146, v146 quad_perm:[1,0,3,2] row_mask:0xf bank_mask:0xf bound_ctrl:1
	v_pk_mul_f32 v[180:181], v[138:139], v[180:181]
	v_pk_fma_f32 v[180:181], v[140:141], v[182:183], v[180:181]
	v_add_f32_dpp v146, v146, v146 quad_perm:[2,3,0,1] row_mask:0xf bank_mask:0xf bound_ctrl:1
	s_waitcnt lgkmcnt(12)
	v_pk_mul_f32 v[198:199], v[198:199], v[206:207] op_sel_hi:[1,0]
	v_add_f32_dpp v146, v146, v146 row_half_mirror row_mask:0xf bank_mask:0xf bound_ctrl:1
	v_pk_mul_f32 v[200:201], v[200:201], v[206:207] op_sel_hi:[1,0]
	v_add_f32 v160, v180, v181
	v_add_f32_dpp v146, v146, v146 row_mirror row_mask:0xf bank_mask:0xf bound_ctrl:1
	v_pk_fma_f32 v[198:199], v[146:147], v[190:191], v[198:199] op_sel_hi:[0,1,1] neg_lo:[1,0,0] neg_hi:[1,0,0]
	v_pk_fma_f32 v[200:201], v[146:147], v[192:193], v[200:201] op_sel_hi:[0,1,1] neg_lo:[1,0,0] neg_hi:[1,0,0]
	v_pk_fma_f32 v[138:139], v[138:139], v[194:195], v[198:199]
	v_pk_fma_f32 v[140:141], v[140:141], v[196:197], v[200:201]
	v_pk_mul_f32 v[144:145], v[138:139], v[208:209]
	v_pk_fma_f32 v[144:145], v[140:141], v[210:211], v[144:145]
	v_add_f32 v146, v144, v145
	ds_read_b128 v[168:171], v5 offset:24832
	ds_read_b128 v[172:175], v5 offset:25088
	ds_read_b128 v[176:179], v5 offset:25344
	ds_read_b128 v[180:183], v5 offset:25600
	ds_read_b32 v184, v9 offset:24576
	ds_read_b128 v[186:189], v5 offset:26112
	v_add_f32_dpp v146, v146, v146 quad_perm:[1,0,3,2] row_mask:0xf bank_mask:0xf bound_ctrl:1
	v_pk_mul_f32 v[202:203], v[138:139], v[202:203]
	v_pk_fma_f32 v[202:203], v[140:141], v[204:205], v[202:203]
	v_add_f32_dpp v146, v146, v146 quad_perm:[2,3,0,1] row_mask:0xf bank_mask:0xf bound_ctrl:1
	s_waitcnt lgkmcnt(12)
	v_pk_mul_f32 v[220:221], v[220:221], v[228:229] op_sel_hi:[1,0]
	v_add_f32_dpp v146, v146, v146 row_half_mirror row_mask:0xf bank_mask:0xf bound_ctrl:1
	v_pk_mul_f32 v[222:223], v[222:223], v[228:229] op_sel_hi:[1,0]
	v_add_f32 v161, v202, v203
	v_add_f32_dpp v146, v146, v146 row_mirror row_mask:0xf bank_mask:0xf bound_ctrl:1
	v_pk_fma_f32 v[220:221], v[146:147], v[212:213], v[220:221] op_sel_hi:[0,1,1] neg_lo:[1,0,0] neg_hi:[1,0,0]
	v_pk_fma_f32 v[222:223], v[146:147], v[214:215], v[222:223] op_sel_hi:[0,1,1] neg_lo:[1,0,0] neg_hi:[1,0,0]
	v_pk_fma_f32 v[138:139], v[138:139], v[216:217], v[220:221]
	v_pk_fma_f32 v[140:141], v[140:141], v[218:219], v[222:223]
	v_pk_mul_f32 v[144:145], v[138:139], v[230:231]
	v_pk_fma_f32 v[144:145], v[140:141], v[232:233], v[144:145]
	v_add_f32 v146, v144, v145
	ds_read_b128 v[190:193], v5 offset:26368
	ds_read_b128 v[194:197], v5 offset:26624
	ds_read_b128 v[198:201], v5 offset:26880
	ds_read_b128 v[202:205], v5 offset:27136
	ds_read_b32 v206, v9 offset:26112
	ds_read_b128 v[208:211], v5 offset:27648
	v_add_f32_dpp v146, v146, v146 quad_perm:[1,0,3,2] row_mask:0xf bank_mask:0xf bound_ctrl:1
	v_pk_mul_f32 v[224:225], v[138:139], v[224:225]
	v_pk_fma_f32 v[224:225], v[140:141], v[226:227], v[224:225]
	v_add_f32_dpp v146, v146, v146 quad_perm:[2,3,0,1] row_mask:0xf bank_mask:0xf bound_ctrl:1
	s_waitcnt lgkmcnt(12)
	v_pk_mul_f32 v[242:243], v[242:243], v[250:251] op_sel_hi:[1,0]
	v_add_f32_dpp v146, v146, v146 row_half_mirror row_mask:0xf bank_mask:0xf bound_ctrl:1
	v_pk_mul_f32 v[244:245], v[244:245], v[250:251] op_sel_hi:[1,0]
	v_add_f32 v162, v224, v225
	v_add_f32_dpp v146, v146, v146 row_mirror row_mask:0xf bank_mask:0xf bound_ctrl:1
	v_pk_fma_f32 v[242:243], v[146:147], v[234:235], v[242:243] op_sel_hi:[0,1,1] neg_lo:[1,0,0] neg_hi:[1,0,0]
	v_pk_fma_f32 v[244:245], v[146:147], v[236:237], v[244:245] op_sel_hi:[0,1,1] neg_lo:[1,0,0] neg_hi:[1,0,0]
	v_pk_fma_f32 v[138:139], v[138:139], v[238:239], v[242:243]
	v_pk_fma_f32 v[140:141], v[140:141], v[240:241], v[244:245]
	v_pk_mul_f32 v[144:145], v[138:139], v[164:165]
	v_pk_fma_f32 v[144:145], v[140:141], v[166:167], v[144:145]
	v_add_f32 v146, v144, v145
	ds_read_b128 v[212:215], v5 offset:27904
	ds_read_b128 v[216:219], v5 offset:28160
	ds_read_b128 v[220:223], v5 offset:28416
	ds_read_b128 v[224:227], v5 offset:28672
	ds_read_b32 v228, v9 offset:27648
	ds_read_b128 v[230:233], v5 offset:29184
	v_add_f32_dpp v146, v146, v146 quad_perm:[1,0,3,2] row_mask:0xf bank_mask:0xf bound_ctrl:1
	v_pk_mul_f32 v[246:247], v[138:139], v[246:247]
	v_pk_fma_f32 v[246:247], v[140:141], v[248:249], v[246:247]
	v_add_f32_dpp v146, v146, v146 quad_perm:[2,3,0,1] row_mask:0xf bank_mask:0xf bound_ctrl:1
	s_waitcnt lgkmcnt(12)
	v_pk_mul_f32 v[176:177], v[176:177], v[184:185] op_sel_hi:[1,0]
	v_add_f32_dpp v146, v146, v146 row_half_mirror row_mask:0xf bank_mask:0xf bound_ctrl:1
	v_pk_mul_f32 v[178:179], v[178:179], v[184:185] op_sel_hi:[1,0]
	v_add_f32 v163, v246, v247
	v_add_f32_dpp v146, v146, v146 row_mirror row_mask:0xf bank_mask:0xf bound_ctrl:1
	v_pk_fma_f32 v[176:177], v[146:147], v[168:169], v[176:177] op_sel_hi:[0,1,1] neg_lo:[1,0,0] neg_hi:[1,0,0]
	v_pk_fma_f32 v[178:179], v[146:147], v[170:171], v[178:179] op_sel_hi:[0,1,1] neg_lo:[1,0,0] neg_hi:[1,0,0]
	v_pk_fma_f32 v[138:139], v[138:139], v[172:173], v[176:177]
	v_pk_fma_f32 v[140:141], v[140:141], v[174:175], v[178:179]
	v_pk_mul_f32 v[144:145], v[138:139], v[186:187]
	v_pk_fma_f32 v[144:145], v[140:141], v[188:189], v[144:145]
	v_add_f32 v146, v144, v145
	v_add_f32_dpp v102, v148, v148 row_mirror row_mask:0xf bank_mask:0x3 bound_ctrl:1
	v_add_f32_dpp v102, v156, v156 row_mirror row_mask:0xf bank_mask:0xc bound_ctrl:1
	v_add_f32_dpp v103, v149, v149 row_mirror row_mask:0xf bank_mask:0x3 bound_ctrl:1
	v_add_f32_dpp v103, v157, v157 row_mirror row_mask:0xf bank_mask:0xc bound_ctrl:1
	v_add_f32_dpp v104, v150, v150 row_mirror row_mask:0xf bank_mask:0x3 bound_ctrl:1
	v_add_f32_dpp v104, v158, v158 row_mirror row_mask:0xf bank_mask:0xc bound_ctrl:1
	v_add_f32_dpp v105, v151, v151 row_mirror row_mask:0xf bank_mask:0x3 bound_ctrl:1
	v_add_f32_dpp v105, v159, v159 row_mirror row_mask:0xf bank_mask:0xc bound_ctrl:1
	v_add_f32_dpp v106, v152, v152 row_mirror row_mask:0xf bank_mask:0x3 bound_ctrl:1
	v_add_f32_dpp v106, v160, v160 row_mirror row_mask:0xf bank_mask:0xc bound_ctrl:1
	v_add_f32_dpp v107, v153, v153 row_mirror row_mask:0xf bank_mask:0x3 bound_ctrl:1
	v_add_f32_dpp v107, v161, v161 row_mirror row_mask:0xf bank_mask:0xc bound_ctrl:1
	v_add_f32_dpp v108, v154, v154 row_mirror row_mask:0xf bank_mask:0x3 bound_ctrl:1
	v_add_f32_dpp v108, v162, v162 row_mirror row_mask:0xf bank_mask:0xc bound_ctrl:1
	v_add_f32_dpp v109, v155, v155 row_mirror row_mask:0xf bank_mask:0x3 bound_ctrl:1
	v_add_f32_dpp v109, v163, v163 row_mirror row_mask:0xf bank_mask:0xc bound_ctrl:1
	v_add_f32_dpp v110, v102, v102 row_half_mirror row_mask:0xf bank_mask:0x5 bound_ctrl:1
	v_add_f32_dpp v110, v106, v106 row_half_mirror row_mask:0xf bank_mask:0xa bound_ctrl:1
	v_add_f32_dpp v111, v103, v103 row_half_mirror row_mask:0xf bank_mask:0x5 bound_ctrl:1
	v_add_f32_dpp v111, v107, v107 row_half_mirror row_mask:0xf bank_mask:0xa bound_ctrl:1
	v_add_f32_dpp v112, v104, v104 row_half_mirror row_mask:0xf bank_mask:0x5 bound_ctrl:1
	v_add_f32_dpp v112, v108, v108 row_half_mirror row_mask:0xf bank_mask:0xa bound_ctrl:1
	v_add_f32_dpp v113, v105, v105 row_half_mirror row_mask:0xf bank_mask:0x5 bound_ctrl:1
	v_add_f32_dpp v113, v109, v109 row_half_mirror row_mask:0xf bank_mask:0xa bound_ctrl:1
	s_mov_b32 vcc_lo, 0xcccccccc
	s_mov_b32 vcc_hi, 0xcccccccc
	v_cndmask_b32 v116, v112, v110, vcc
	v_cndmask_b32 v117, v113, v111, vcc
	v_cndmask_b32 v114, v110, v112, vcc
	v_cndmask_b32 v115, v111, v113, vcc
	v_add_f32_dpp v114, v116, v114 quad_perm:[2,3,0,1] row_mask:0xf bank_mask:0xf bound_ctrl:1
	v_add_f32_dpp v115, v117, v115 quad_perm:[2,3,0,1] row_mask:0xf bank_mask:0xf bound_ctrl:1
	s_mov_b32 vcc_lo, 0xaaaaaaaa
	s_mov_b32 vcc_hi, 0xaaaaaaaa
	v_cndmask_b32 v116, v115, v114, vcc
	v_cndmask_b32 v117, v114, v115, vcc
	s_nop 0
	v_add_f32_dpp v18, v116, v117 quad_perm:[1,0,3,2] row_mask:0xf bank_mask:0xf bound_ctrl:1
	ds_read_b128 v[234:237], v5 offset:29440
	ds_read_b128 v[238:241], v5 offset:29696
	ds_read_b128 v[242:245], v5 offset:29952
	ds_read_b128 v[246:249], v5 offset:30208
	ds_read_b32 v250, v9 offset:29184
	ds_read_b128 v[164:167], v5 offset:30720
	v_add_f32_dpp v146, v146, v146 quad_perm:[1,0,3,2] row_mask:0xf bank_mask:0xf bound_ctrl:1
	v_pk_mul_f32 v[180:181], v[138:139], v[180:181]
	v_pk_fma_f32 v[180:181], v[140:141], v[182:183], v[180:181]
	v_add_f32_dpp v146, v146, v146 quad_perm:[2,3,0,1] row_mask:0xf bank_mask:0xf bound_ctrl:1
	s_waitcnt lgkmcnt(12)
	v_pk_mul_f32 v[198:199], v[198:199], v[206:207] op_sel_hi:[1,0]
	v_add_f32_dpp v146, v146, v146 row_half_mirror row_mask:0xf bank_mask:0xf bound_ctrl:1
	v_pk_mul_f32 v[200:201], v[200:201], v[206:207] op_sel_hi:[1,0]
	v_add_f32 v148, v180, v181
	v_add_f32_dpp v146, v146, v146 row_mirror row_mask:0xf bank_mask:0xf bound_ctrl:1
	v_pk_fma_f32 v[198:199], v[146:147], v[190:191], v[198:199] op_sel_hi:[0,1,1] neg_lo:[1,0,0] neg_hi:[1,0,0]
	v_pk_fma_f32 v[200:201], v[146:147], v[192:193], v[200:201] op_sel_hi:[0,1,1] neg_lo:[1,0,0] neg_hi:[1,0,0]
	v_pk_fma_f32 v[138:139], v[138:139], v[194:195], v[198:199]
	v_pk_fma_f32 v[140:141], v[140:141], v[196:197], v[200:201]
	v_pk_mul_f32 v[144:145], v[138:139], v[208:209]
	v_pk_fma_f32 v[144:145], v[140:141], v[210:211], v[144:145]
	v_add_f32 v146, v144, v145
	ds_read_b128 v[168:171], v5 offset:30976
	ds_read_b128 v[172:175], v5 offset:31232
	ds_read_b128 v[176:179], v5 offset:31488
	ds_read_b128 v[180:183], v5 offset:31744
	ds_read_b32 v184, v9 offset:30720
	ds_read_b128 v[186:189], v5 offset:32256
	v_add_f32_dpp v146, v146, v146 quad_perm:[1,0,3,2] row_mask:0xf bank_mask:0xf bound_ctrl:1
	v_pk_mul_f32 v[202:203], v[138:139], v[202:203]
	v_pk_fma_f32 v[202:203], v[140:141], v[204:205], v[202:203]
	v_add_f32_dpp v146, v146, v146 quad_perm:[2,3,0,1] row_mask:0xf bank_mask:0xf bound_ctrl:1
	s_waitcnt lgkmcnt(12)
	v_pk_mul_f32 v[220:221], v[220:221], v[228:229] op_sel_hi:[1,0]
	v_add_f32_dpp v146, v146, v146 row_half_mirror row_mask:0xf bank_mask:0xf bound_ctrl:1
	v_pk_mul_f32 v[222:223], v[222:223], v[228:229] op_sel_hi:[1,0]
	v_add_f32 v149, v202, v203
	v_add_f32_dpp v146, v146, v146 row_mirror row_mask:0xf bank_mask:0xf bound_ctrl:1
	v_pk_fma_f32 v[220:221], v[146:147], v[212:213], v[220:221] op_sel_hi:[0,1,1] neg_lo:[1,0,0] neg_hi:[1,0,0]
	v_pk_fma_f32 v[222:223], v[146:147], v[214:215], v[222:223] op_sel_hi:[0,1,1] neg_lo:[1,0,0] neg_hi:[1,0,0]
	v_pk_fma_f32 v[138:139], v[138:139], v[216:217], v[220:221]
	v_pk_fma_f32 v[140:141], v[140:141], v[218:219], v[222:223]
	v_pk_mul_f32 v[144:145], v[138:139], v[230:231]
	v_pk_fma_f32 v[144:145], v[140:141], v[232:233], v[144:145]
	v_add_f32 v146, v144, v145
	ds_read_b128 v[190:193], v5 offset:32512
	ds_read_b128 v[194:197], v5 offset:32768
	ds_read_b128 v[198:201], v5 offset:33024
	ds_read_b128 v[202:205], v5 offset:33280
	ds_read_b32 v206, v9 offset:32256
	ds_read_b128 v[208:211], v5 offset:33792
	v_add_f32_dpp v146, v146, v146 quad_perm:[1,0,3,2] row_mask:0xf bank_mask:0xf bound_ctrl:1
	v_pk_mul_f32 v[224:225], v[138:139], v[224:225]
	v_pk_fma_f32 v[224:225], v[140:141], v[226:227], v[224:225]
	v_add_f32_dpp v146, v146, v146 quad_perm:[2,3,0,1] row_mask:0xf bank_mask:0xf bound_ctrl:1
	s_waitcnt lgkmcnt(12)
	v_pk_mul_f32 v[242:243], v[242:243], v[250:251] op_sel_hi:[1,0]
	v_add_f32_dpp v146, v146, v146 row_half_mirror row_mask:0xf bank_mask:0xf bound_ctrl:1
	v_pk_mul_f32 v[244:245], v[244:245], v[250:251] op_sel_hi:[1,0]
	v_add_f32 v150, v224, v225
	v_add_f32_dpp v146, v146, v146 row_mirror row_mask:0xf bank_mask:0xf bound_ctrl:1
	v_pk_fma_f32 v[242:243], v[146:147], v[234:235], v[242:243] op_sel_hi:[0,1,1] neg_lo:[1,0,0] neg_hi:[1,0,0]
	v_pk_fma_f32 v[244:245], v[146:147], v[236:237], v[244:245] op_sel_hi:[0,1,1] neg_lo:[1,0,0] neg_hi:[1,0,0]
	v_pk_fma_f32 v[138:139], v[138:139], v[238:239], v[242:243]
	v_pk_fma_f32 v[140:141], v[140:141], v[240:241], v[244:245]
	v_pk_mul_f32 v[144:145], v[138:139], v[164:165]
	v_pk_fma_f32 v[144:145], v[140:141], v[166:167], v[144:145]
	v_add_f32 v146, v144, v145
	ds_read_b128 v[212:215], v5 offset:34048
	ds_read_b128 v[216:219], v5 offset:34304
	ds_read_b128 v[220:223], v5 offset:34560
	ds_read_b128 v[224:227], v5 offset:34816
	ds_read_b32 v228, v9 offset:33792
	ds_read_b128 v[230:233], v5 offset:35328
	v_add_f32_dpp v146, v146, v146 quad_perm:[1,0,3,2] row_mask:0xf bank_mask:0xf bound_ctrl:1
	v_pk_mul_f32 v[246:247], v[138:139], v[246:247]
	v_pk_fma_f32 v[246:247], v[140:141], v[248:249], v[246:247]
	v_add_f32_dpp v146, v146, v146 quad_perm:[2,3,0,1] row_mask:0xf bank_mask:0xf bound_ctrl:1
	s_waitcnt lgkmcnt(12)
	v_pk_mul_f32 v[176:177], v[176:177], v[184:185] op_sel_hi:[1,0]
	v_add_f32_dpp v146, v146, v146 row_half_mirror row_mask:0xf bank_mask:0xf bound_ctrl:1
	v_pk_mul_f32 v[178:179], v[178:179], v[184:185] op_sel_hi:[1,0]
	v_add_f32 v151, v246, v247
	v_add_f32_dpp v146, v146, v146 row_mirror row_mask:0xf bank_mask:0xf bound_ctrl:1
	v_pk_fma_f32 v[176:177], v[146:147], v[168:169], v[176:177] op_sel_hi:[0,1,1] neg_lo:[1,0,0] neg_hi:[1,0,0]
	v_pk_fma_f32 v[178:179], v[146:147], v[170:171], v[178:179] op_sel_hi:[0,1,1] neg_lo:[1,0,0] neg_hi:[1,0,0]
	v_pk_fma_f32 v[138:139], v[138:139], v[172:173], v[176:177]
	v_pk_fma_f32 v[140:141], v[140:141], v[174:175], v[178:179]
	v_pk_mul_f32 v[144:145], v[138:139], v[186:187]
	v_pk_fma_f32 v[144:145], v[140:141], v[188:189], v[144:145]
	v_add_f32 v146, v144, v145
	ds_read_b128 v[234:237], v5 offset:35584
	ds_read_b128 v[238:241], v5 offset:35840
	ds_read_b128 v[242:245], v5 offset:36096
	ds_read_b128 v[246:249], v5 offset:36352
	ds_read_b32 v250, v9 offset:35328
	ds_read_b128 v[164:167], v5 offset:36864
	v_add_f32_dpp v146, v146, v146 quad_perm:[1,0,3,2] row_mask:0xf bank_mask:0xf bound_ctrl:1
	v_pk_mul_f32 v[180:181], v[138:139], v[180:181]
	v_pk_fma_f32 v[180:181], v[140:141], v[182:183], v[180:181]
	v_add_f32_dpp v146, v146, v146 quad_perm:[2,3,0,1] row_mask:0xf bank_mask:0xf bound_ctrl:1
	s_waitcnt lgkmcnt(12)
	v_pk_mul_f32 v[198:199], v[198:199], v[206:207] op_sel_hi:[1,0]
	v_add_f32_dpp v146, v146, v146 row_half_mirror row_mask:0xf bank_mask:0xf bound_ctrl:1
	v_pk_mul_f32 v[200:201], v[200:201], v[206:207] op_sel_hi:[1,0]
	v_add_f32 v152, v180, v181
	v_add_f32_dpp v146, v146, v146 row_mirror row_mask:0xf bank_mask:0xf bound_ctrl:1
	v_pk_fma_f32 v[198:199], v[146:147], v[190:191], v[198:199] op_sel_hi:[0,1,1] neg_lo:[1,0,0] neg_hi:[1,0,0]
	v_pk_fma_f32 v[200:201], v[146:147], v[192:193], v[200:201] op_sel_hi:[0,1,1] neg_lo:[1,0,0] neg_hi:[1,0,0]
	v_pk_fma_f32 v[138:139], v[138:139], v[194:195], v[198:199]
	v_pk_fma_f32 v[140:141], v[140:141], v[196:197], v[200:201]
	v_pk_mul_f32 v[144:145], v[138:139], v[208:209]
	v_pk_fma_f32 v[144:145], v[140:141], v[210:211], v[144:145]
	v_add_f32 v146, v144, v145
	ds_read_b128 v[168:171], v5 offset:37120
	ds_read_b128 v[172:175], v5 offset:37376
	ds_read_b128 v[176:179], v5 offset:37632
	ds_read_b128 v[180:183], v5 offset:37888
	ds_read_b32 v184, v9 offset:36864
	ds_read_b128 v[186:189], v5 offset:38400
	v_add_f32_dpp v146, v146, v146 quad_perm:[1,0,3,2] row_mask:0xf bank_mask:0xf bound_ctrl:1
	v_pk_mul_f32 v[202:203], v[138:139], v[202:203]
	v_pk_fma_f32 v[202:203], v[140:141], v[204:205], v[202:203]
	v_add_f32_dpp v146, v146, v146 quad_perm:[2,3,0,1] row_mask:0xf bank_mask:0xf bound_ctrl:1
	s_waitcnt lgkmcnt(12)
	v_pk_mul_f32 v[220:221], v[220:221], v[228:229] op_sel_hi:[1,0]
	v_add_f32_dpp v146, v146, v146 row_half_mirror row_mask:0xf bank_mask:0xf bound_ctrl:1
	v_pk_mul_f32 v[222:223], v[222:223], v[228:229] op_sel_hi:[1,0]
	v_add_f32 v153, v202, v203
	v_add_f32_dpp v146, v146, v146 row_mirror row_mask:0xf bank_mask:0xf bound_ctrl:1
	v_pk_fma_f32 v[220:221], v[146:147], v[212:213], v[220:221] op_sel_hi:[0,1,1] neg_lo:[1,0,0] neg_hi:[1,0,0]
	v_pk_fma_f32 v[222:223], v[146:147], v[214:215], v[222:223] op_sel_hi:[0,1,1] neg_lo:[1,0,0] neg_hi:[1,0,0]
	v_pk_fma_f32 v[138:139], v[138:139], v[216:217], v[220:221]
	v_pk_fma_f32 v[140:141], v[140:141], v[218:219], v[222:223]
	v_pk_mul_f32 v[144:145], v[138:139], v[230:231]
	v_pk_fma_f32 v[144:145], v[140:141], v[232:233], v[144:145]
	v_add_f32 v146, v144, v145
	ds_read_b128 v[190:193], v5 offset:38656
	ds_read_b128 v[194:197], v5 offset:38912
	ds_read_b128 v[198:201], v5 offset:39168
	ds_read_b128 v[202:205], v5 offset:39424
	ds_read_b32 v206, v9 offset:38400
	ds_read_b128 v[208:211], v5 offset:39936
	v_add_f32_dpp v146, v146, v146 quad_perm:[1,0,3,2] row_mask:0xf bank_mask:0xf bound_ctrl:1
	v_pk_mul_f32 v[224:225], v[138:139], v[224:225]
	v_pk_fma_f32 v[224:225], v[140:141], v[226:227], v[224:225]
	v_add_f32_dpp v146, v146, v146 quad_perm:[2,3,0,1] row_mask:0xf bank_mask:0xf bound_ctrl:1
	s_waitcnt lgkmcnt(12)
	v_pk_mul_f32 v[242:243], v[242:243], v[250:251] op_sel_hi:[1,0]
	v_add_f32_dpp v146, v146, v146 row_half_mirror row_mask:0xf bank_mask:0xf bound_ctrl:1
	v_pk_mul_f32 v[244:245], v[244:245], v[250:251] op_sel_hi:[1,0]
	v_add_f32 v154, v224, v225
	v_add_f32_dpp v146, v146, v146 row_mirror row_mask:0xf bank_mask:0xf bound_ctrl:1
	v_pk_fma_f32 v[242:243], v[146:147], v[234:235], v[242:243] op_sel_hi:[0,1,1] neg_lo:[1,0,0] neg_hi:[1,0,0]
	v_pk_fma_f32 v[244:245], v[146:147], v[236:237], v[244:245] op_sel_hi:[0,1,1] neg_lo:[1,0,0] neg_hi:[1,0,0]
	v_pk_fma_f32 v[138:139], v[138:139], v[238:239], v[242:243]
	v_pk_fma_f32 v[140:141], v[140:141], v[240:241], v[244:245]
	v_pk_mul_f32 v[144:145], v[138:139], v[164:165]
	v_pk_fma_f32 v[144:145], v[140:141], v[166:167], v[144:145]
	v_add_f32 v146, v144, v145
	ds_read_b128 v[212:215], v5 offset:40192
	ds_read_b128 v[216:219], v5 offset:40448
	ds_read_b128 v[220:223], v5 offset:40704
	ds_read_b128 v[224:227], v5 offset:40960
	ds_read_b32 v228, v9 offset:39936
	ds_read_b128 v[230:233], v5 offset:41472
	v_add_f32_dpp v146, v146, v146 quad_perm:[1,0,3,2] row_mask:0xf bank_mask:0xf bound_ctrl:1
	v_pk_mul_f32 v[246:247], v[138:139], v[246:247]
	v_pk_fma_f32 v[246:247], v[140:141], v[248:249], v[246:247]
	v_add_f32_dpp v146, v146, v146 quad_perm:[2,3,0,1] row_mask:0xf bank_mask:0xf bound_ctrl:1
	s_waitcnt lgkmcnt(12)
	v_pk_mul_f32 v[176:177], v[176:177], v[184:185] op_sel_hi:[1,0]
	v_add_f32_dpp v146, v146, v146 row_half_mirror row_mask:0xf bank_mask:0xf bound_ctrl:1
	v_pk_mul_f32 v[178:179], v[178:179], v[184:185] op_sel_hi:[1,0]
	v_add_f32 v155, v246, v247
	v_add_f32_dpp v146, v146, v146 row_mirror row_mask:0xf bank_mask:0xf bound_ctrl:1
	v_pk_fma_f32 v[176:177], v[146:147], v[168:169], v[176:177] op_sel_hi:[0,1,1] neg_lo:[1,0,0] neg_hi:[1,0,0]
	v_pk_fma_f32 v[178:179], v[146:147], v[170:171], v[178:179] op_sel_hi:[0,1,1] neg_lo:[1,0,0] neg_hi:[1,0,0]
	v_pk_fma_f32 v[138:139], v[138:139], v[172:173], v[176:177]
	v_pk_fma_f32 v[140:141], v[140:141], v[174:175], v[178:179]
	v_pk_mul_f32 v[144:145], v[138:139], v[186:187]
	v_pk_fma_f32 v[144:145], v[140:141], v[188:189], v[144:145]
	v_add_f32 v146, v144, v145
	ds_read_b128 v[234:237], v5 offset:41728
	ds_read_b128 v[238:241], v5 offset:41984
	ds_read_b128 v[242:245], v5 offset:42240
	ds_read_b128 v[246:249], v5 offset:42496
	ds_read_b32 v250, v9 offset:41472
	ds_read_b128 v[164:167], v5 offset:43008
	v_add_f32_dpp v146, v146, v146 quad_perm:[1,0,3,2] row_mask:0xf bank_mask:0xf bound_ctrl:1
	v_pk_mul_f32 v[180:181], v[138:139], v[180:181]
	v_pk_fma_f32 v[180:181], v[140:141], v[182:183], v[180:181]
	v_add_f32_dpp v146, v146, v146 quad_perm:[2,3,0,1] row_mask:0xf bank_mask:0xf bound_ctrl:1
	s_waitcnt lgkmcnt(12)
	v_pk_mul_f32 v[198:199], v[198:199], v[206:207] op_sel_hi:[1,0]
	v_add_f32_dpp v146, v146, v146 row_half_mirror row_mask:0xf bank_mask:0xf bound_ctrl:1
	v_pk_mul_f32 v[200:201], v[200:201], v[206:207] op_sel_hi:[1,0]
	v_add_f32 v156, v180, v181
	v_add_f32_dpp v146, v146, v146 row_mirror row_mask:0xf bank_mask:0xf bound_ctrl:1
	v_pk_fma_f32 v[198:199], v[146:147], v[190:191], v[198:199] op_sel_hi:[0,1,1] neg_lo:[1,0,0] neg_hi:[1,0,0]
	v_pk_fma_f32 v[200:201], v[146:147], v[192:193], v[200:201] op_sel_hi:[0,1,1] neg_lo:[1,0,0] neg_hi:[1,0,0]
	v_pk_fma_f32 v[138:139], v[138:139], v[194:195], v[198:199]
	v_pk_fma_f32 v[140:141], v[140:141], v[196:197], v[200:201]
	v_pk_mul_f32 v[144:145], v[138:139], v[208:209]
	v_pk_fma_f32 v[144:145], v[140:141], v[210:211], v[144:145]
	v_add_f32 v146, v144, v145
	ds_read_b128 v[168:171], v5 offset:43264
	ds_read_b128 v[172:175], v5 offset:43520
	ds_read_b128 v[176:179], v5 offset:43776
	ds_read_b128 v[180:183], v5 offset:44032
	ds_read_b32 v184, v9 offset:43008
	ds_read_b128 v[186:189], v5 offset:44544
	v_add_f32_dpp v146, v146, v146 quad_perm:[1,0,3,2] row_mask:0xf bank_mask:0xf bound_ctrl:1
	v_pk_mul_f32 v[202:203], v[138:139], v[202:203]
	v_pk_fma_f32 v[202:203], v[140:141], v[204:205], v[202:203]
	v_add_f32_dpp v146, v146, v146 quad_perm:[2,3,0,1] row_mask:0xf bank_mask:0xf bound_ctrl:1
	s_waitcnt lgkmcnt(12)
	v_pk_mul_f32 v[220:221], v[220:221], v[228:229] op_sel_hi:[1,0]
	v_add_f32_dpp v146, v146, v146 row_half_mirror row_mask:0xf bank_mask:0xf bound_ctrl:1
	v_pk_mul_f32 v[222:223], v[222:223], v[228:229] op_sel_hi:[1,0]
	v_add_f32 v157, v202, v203
	v_add_f32_dpp v146, v146, v146 row_mirror row_mask:0xf bank_mask:0xf bound_ctrl:1
	v_pk_fma_f32 v[220:221], v[146:147], v[212:213], v[220:221] op_sel_hi:[0,1,1] neg_lo:[1,0,0] neg_hi:[1,0,0]
	v_pk_fma_f32 v[222:223], v[146:147], v[214:215], v[222:223] op_sel_hi:[0,1,1] neg_lo:[1,0,0] neg_hi:[1,0,0]
	v_pk_fma_f32 v[138:139], v[138:139], v[216:217], v[220:221]
	v_pk_fma_f32 v[140:141], v[140:141], v[218:219], v[222:223]
	v_pk_mul_f32 v[144:145], v[138:139], v[230:231]
	v_pk_fma_f32 v[144:145], v[140:141], v[232:233], v[144:145]
	v_add_f32 v146, v144, v145
	ds_read_b128 v[190:193], v5 offset:44800
	ds_read_b128 v[194:197], v5 offset:45056
	ds_read_b128 v[198:201], v5 offset:45312
	ds_read_b128 v[202:205], v5 offset:45568
	ds_read_b32 v206, v9 offset:44544
	ds_read_b128 v[208:211], v5 offset:46080
	v_add_f32_dpp v146, v146, v146 quad_perm:[1,0,3,2] row_mask:0xf bank_mask:0xf bound_ctrl:1
	v_pk_mul_f32 v[224:225], v[138:139], v[224:225]
	v_pk_fma_f32 v[224:225], v[140:141], v[226:227], v[224:225]
	v_add_f32_dpp v146, v146, v146 quad_perm:[2,3,0,1] row_mask:0xf bank_mask:0xf bound_ctrl:1
	s_waitcnt lgkmcnt(12)
	v_pk_mul_f32 v[242:243], v[242:243], v[250:251] op_sel_hi:[1,0]
	v_add_f32_dpp v146, v146, v146 row_half_mirror row_mask:0xf bank_mask:0xf bound_ctrl:1
	v_pk_mul_f32 v[244:245], v[244:245], v[250:251] op_sel_hi:[1,0]
	v_add_f32 v158, v224, v225
	v_add_f32_dpp v146, v146, v146 row_mirror row_mask:0xf bank_mask:0xf bound_ctrl:1
	v_pk_fma_f32 v[242:243], v[146:147], v[234:235], v[242:243] op_sel_hi:[0,1,1] neg_lo:[1,0,0] neg_hi:[1,0,0]
	v_pk_fma_f32 v[244:245], v[146:147], v[236:237], v[244:245] op_sel_hi:[0,1,1] neg_lo:[1,0,0] neg_hi:[1,0,0]
	v_pk_fma_f32 v[138:139], v[138:139], v[238:239], v[242:243]
	v_pk_fma_f32 v[140:141], v[140:141], v[240:241], v[244:245]
	v_pk_mul_f32 v[144:145], v[138:139], v[164:165]
	v_pk_fma_f32 v[144:145], v[140:141], v[166:167], v[144:145]
	v_add_f32 v146, v144, v145
	ds_read_b128 v[212:215], v5 offset:46336
	ds_read_b128 v[216:219], v5 offset:46592
	ds_read_b128 v[220:223], v5 offset:46848
	ds_read_b128 v[224:227], v5 offset:47104
	ds_read_b32 v228, v9 offset:46080
	ds_read_b128 v[230:233], v5 offset:47616
	v_add_f32_dpp v146, v146, v146 quad_perm:[1,0,3,2] row_mask:0xf bank_mask:0xf bound_ctrl:1
	v_pk_mul_f32 v[246:247], v[138:139], v[246:247]
	v_pk_fma_f32 v[246:247], v[140:141], v[248:249], v[246:247]
	v_add_f32_dpp v146, v146, v146 quad_perm:[2,3,0,1] row_mask:0xf bank_mask:0xf bound_ctrl:1
	s_waitcnt lgkmcnt(12)
	v_pk_mul_f32 v[176:177], v[176:177], v[184:185] op_sel_hi:[1,0]
	v_add_f32_dpp v146, v146, v146 row_half_mirror row_mask:0xf bank_mask:0xf bound_ctrl:1
	v_pk_mul_f32 v[178:179], v[178:179], v[184:185] op_sel_hi:[1,0]
	v_add_f32 v159, v246, v247
	v_add_f32_dpp v146, v146, v146 row_mirror row_mask:0xf bank_mask:0xf bound_ctrl:1
	v_pk_fma_f32 v[176:177], v[146:147], v[168:169], v[176:177] op_sel_hi:[0,1,1] neg_lo:[1,0,0] neg_hi:[1,0,0]
	v_pk_fma_f32 v[178:179], v[146:147], v[170:171], v[178:179] op_sel_hi:[0,1,1] neg_lo:[1,0,0] neg_hi:[1,0,0]
	v_pk_fma_f32 v[138:139], v[138:139], v[172:173], v[176:177]
	v_pk_fma_f32 v[140:141], v[140:141], v[174:175], v[178:179]
	v_pk_mul_f32 v[144:145], v[138:139], v[186:187]
	v_pk_fma_f32 v[144:145], v[140:141], v[188:189], v[144:145]
	v_add_f32 v146, v144, v145
	ds_read_b128 v[234:237], v5 offset:47872
	ds_read_b128 v[238:241], v5 offset:48128
	ds_read_b128 v[242:245], v5 offset:48384
	ds_read_b128 v[246:249], v5 offset:48640
	ds_read_b32 v250, v9 offset:47616
	v_add_f32_dpp v146, v146, v146 quad_perm:[1,0,3,2] row_mask:0xf bank_mask:0xf bound_ctrl:1
	v_pk_mul_f32 v[180:181], v[138:139], v[180:181]
	v_pk_fma_f32 v[180:181], v[140:141], v[182:183], v[180:181]
	v_add_f32_dpp v146, v146, v146 quad_perm:[2,3,0,1] row_mask:0xf bank_mask:0xf bound_ctrl:1
	s_waitcnt lgkmcnt(11)
	v_pk_mul_f32 v[198:199], v[198:199], v[206:207] op_sel_hi:[1,0]
	v_add_f32_dpp v146, v146, v146 row_half_mirror row_mask:0xf bank_mask:0xf bound_ctrl:1
	v_pk_mul_f32 v[200:201], v[200:201], v[206:207] op_sel_hi:[1,0]
	v_add_f32 v160, v180, v181
	v_add_f32_dpp v146, v146, v146 row_mirror row_mask:0xf bank_mask:0xf bound_ctrl:1
	v_pk_fma_f32 v[198:199], v[146:147], v[190:191], v[198:199] op_sel_hi:[0,1,1] neg_lo:[1,0,0] neg_hi:[1,0,0]
	v_pk_fma_f32 v[200:201], v[146:147], v[192:193], v[200:201] op_sel_hi:[0,1,1] neg_lo:[1,0,0] neg_hi:[1,0,0]
	v_pk_fma_f32 v[138:139], v[138:139], v[194:195], v[198:199]
	v_pk_fma_f32 v[140:141], v[140:141], v[196:197], v[200:201]
	v_pk_mul_f32 v[144:145], v[138:139], v[208:209]
	v_pk_fma_f32 v[144:145], v[140:141], v[210:211], v[144:145]
	v_add_f32 v146, v144, v145
	s_nop 1
	v_add_f32_dpp v146, v146, v146 quad_perm:[1,0,3,2] row_mask:0xf bank_mask:0xf bound_ctrl:1
	v_pk_mul_f32 v[202:203], v[138:139], v[202:203]
	v_pk_fma_f32 v[202:203], v[140:141], v[204:205], v[202:203]
	v_add_f32_dpp v146, v146, v146 quad_perm:[2,3,0,1] row_mask:0xf bank_mask:0xf bound_ctrl:1
	s_waitcnt lgkmcnt(5)
	v_pk_mul_f32 v[220:221], v[220:221], v[228:229] op_sel_hi:[1,0]
	v_add_f32_dpp v146, v146, v146 row_half_mirror row_mask:0xf bank_mask:0xf bound_ctrl:1
	v_pk_mul_f32 v[222:223], v[222:223], v[228:229] op_sel_hi:[1,0]
	v_add_f32 v161, v202, v203
	v_add_f32_dpp v146, v146, v146 row_mirror row_mask:0xf bank_mask:0xf bound_ctrl:1
	v_pk_fma_f32 v[220:221], v[146:147], v[212:213], v[220:221] op_sel_hi:[0,1,1] neg_lo:[1,0,0] neg_hi:[1,0,0]
	v_pk_fma_f32 v[222:223], v[146:147], v[214:215], v[222:223] op_sel_hi:[0,1,1] neg_lo:[1,0,0] neg_hi:[1,0,0]
	v_pk_fma_f32 v[138:139], v[138:139], v[216:217], v[220:221]
	v_pk_fma_f32 v[140:141], v[140:141], v[218:219], v[222:223]
	v_pk_mul_f32 v[144:145], v[138:139], v[230:231]
	v_pk_fma_f32 v[144:145], v[140:141], v[232:233], v[144:145]
	v_add_f32 v146, v144, v145
	s_nop 1
	v_add_f32_dpp v146, v146, v146 quad_perm:[1,0,3,2] row_mask:0xf bank_mask:0xf bound_ctrl:1
	v_pk_mul_f32 v[224:225], v[138:139], v[224:225]
	v_pk_fma_f32 v[224:225], v[140:141], v[226:227], v[224:225]
	v_add_f32_dpp v146, v146, v146 quad_perm:[2,3,0,1] row_mask:0xf bank_mask:0xf bound_ctrl:1
	s_waitcnt lgkmcnt(0)
	v_pk_mul_f32 v[242:243], v[242:243], v[250:251] op_sel_hi:[1,0]
	v_add_f32_dpp v146, v146, v146 row_half_mirror row_mask:0xf bank_mask:0xf bound_ctrl:1
	v_pk_mul_f32 v[244:245], v[244:245], v[250:251] op_sel_hi:[1,0]
	v_add_f32 v162, v224, v225
	v_add_f32_dpp v146, v146, v146 row_mirror row_mask:0xf bank_mask:0xf bound_ctrl:1
	v_pk_fma_f32 v[242:243], v[146:147], v[234:235], v[242:243] op_sel_hi:[0,1,1] neg_lo:[1,0,0] neg_hi:[1,0,0]
	v_pk_fma_f32 v[244:245], v[146:147], v[236:237], v[244:245] op_sel_hi:[0,1,1] neg_lo:[1,0,0] neg_hi:[1,0,0]
	v_pk_fma_f32 v[138:139], v[138:139], v[238:239], v[242:243]
	v_pk_fma_f32 v[140:141], v[140:141], v[240:241], v[244:245]
	v_pk_mul_f32 v[246:247], v[138:139], v[246:247]
	v_pk_fma_f32 v[246:247], v[140:141], v[248:249], v[246:247]
	v_add_f32 v163, v246, v247
	s_nop 0
	v_add_f32_dpp v102, v148, v148 row_mirror row_mask:0xf bank_mask:0x3 bound_ctrl:1
	v_add_f32_dpp v102, v156, v156 row_mirror row_mask:0xf bank_mask:0xc bound_ctrl:1
	v_add_f32_dpp v103, v149, v149 row_mirror row_mask:0xf bank_mask:0x3 bound_ctrl:1
	v_add_f32_dpp v103, v157, v157 row_mirror row_mask:0xf bank_mask:0xc bound_ctrl:1
	v_add_f32_dpp v104, v150, v150 row_mirror row_mask:0xf bank_mask:0x3 bound_ctrl:1
	v_add_f32_dpp v104, v158, v158 row_mirror row_mask:0xf bank_mask:0xc bound_ctrl:1
	v_add_f32_dpp v105, v151, v151 row_mirror row_mask:0xf bank_mask:0x3 bound_ctrl:1
	v_add_f32_dpp v105, v159, v159 row_mirror row_mask:0xf bank_mask:0xc bound_ctrl:1
	v_add_f32_dpp v106, v152, v152 row_mirror row_mask:0xf bank_mask:0x3 bound_ctrl:1
	v_add_f32_dpp v106, v160, v160 row_mirror row_mask:0xf bank_mask:0xc bound_ctrl:1
	v_add_f32_dpp v107, v153, v153 row_mirror row_mask:0xf bank_mask:0x3 bound_ctrl:1
	v_add_f32_dpp v107, v161, v161 row_mirror row_mask:0xf bank_mask:0xc bound_ctrl:1
	v_add_f32_dpp v108, v154, v154 row_mirror row_mask:0xf bank_mask:0x3 bound_ctrl:1
	v_add_f32_dpp v108, v162, v162 row_mirror row_mask:0xf bank_mask:0xc bound_ctrl:1
	v_add_f32_dpp v109, v155, v155 row_mirror row_mask:0xf bank_mask:0x3 bound_ctrl:1
	v_add_f32_dpp v109, v163, v163 row_mirror row_mask:0xf bank_mask:0xc bound_ctrl:1
	v_add_f32_dpp v110, v102, v102 row_half_mirror row_mask:0xf bank_mask:0x5 bound_ctrl:1
	v_add_f32_dpp v110, v106, v106 row_half_mirror row_mask:0xf bank_mask:0xa bound_ctrl:1
	v_add_f32_dpp v111, v103, v103 row_half_mirror row_mask:0xf bank_mask:0x5 bound_ctrl:1
	v_add_f32_dpp v111, v107, v107 row_half_mirror row_mask:0xf bank_mask:0xa bound_ctrl:1
	v_add_f32_dpp v112, v104, v104 row_half_mirror row_mask:0xf bank_mask:0x5 bound_ctrl:1
	v_add_f32_dpp v112, v108, v108 row_half_mirror row_mask:0xf bank_mask:0xa bound_ctrl:1
	v_add_f32_dpp v113, v105, v105 row_half_mirror row_mask:0xf bank_mask:0x5 bound_ctrl:1
	v_add_f32_dpp v113, v109, v109 row_half_mirror row_mask:0xf bank_mask:0xa bound_ctrl:1
	s_mov_b32 vcc_lo, 0xcccccccc
	s_mov_b32 vcc_hi, 0xcccccccc
	v_cndmask_b32 v116, v112, v110, vcc
	v_cndmask_b32 v117, v113, v111, vcc
	v_cndmask_b32 v114, v110, v112, vcc
	v_cndmask_b32 v115, v111, v113, vcc
	v_add_f32_dpp v114, v116, v114 quad_perm:[2,3,0,1] row_mask:0xf bank_mask:0xf bound_ctrl:1
	v_add_f32_dpp v115, v117, v115 quad_perm:[2,3,0,1] row_mask:0xf bank_mask:0xf bound_ctrl:1
	s_mov_b32 vcc_lo, 0xaaaaaaaa
	s_mov_b32 vcc_hi, 0xaaaaaaaa
	v_cndmask_b32 v116, v115, v114, vcc
	v_cndmask_b32 v117, v114, v115, vcc
	s_nop 0
	v_add_f32_dpp v19, v116, v117 quad_perm:[1,0,3,2] row_mask:0xf bank_mask:0xf bound_ctrl:1

; #define SCAN_BAR() asm volatile("s_barrier" ::: "memory")
; __device__ __forceinline__ void scan_unit(const Ctx& C0, const float* scn, int T, int quarter, const float* S0, float* Sout, unsigned char* obase, int mode) {
;     ...
;             if (mode == 0) { *(float*)(obase + (size_t)(k * 32 + q) * UPITCH_B + rl * 4) = osel0; *(float*)(obase + (size_t)(k * 32 + 16 + q) * UPITCH_B + rl * 4) = osel1; }
;             SCAN_BAR();
	global_store_dword v6, v18, s[98:99]
	s_add_u32 s98, s98, 0x2b000
	s_addc_u32 s99, s99, 0
	global_store_dword v6, v19, s[98:99]
	s_add_u32 s98, s98, 0x2b000
	s_addc_u32 s99, s99, 0
	s_barrier
	ds_read_b128 v[164:167], v10 offset:0
	ds_read_b128 v[168:171], v10 offset:256
	ds_read_b128 v[172:175], v10 offset:512
	ds_read_b128 v[176:179], v10 offset:768
	ds_read_b128 v[180:183], v10 offset:1024
	ds_read_b32 v184, v11 offset:0
	ds_read_b128 v[186:189], v10 offset:1536
	ds_read_b128 v[190:193], v10 offset:1792
	ds_read_b128 v[194:197], v10 offset:2048
	ds_read_b128 v[198:201], v10 offset:2304
	ds_read_b128 v[202:205], v10 offset:2560
	ds_read_b32 v206, v11 offset:1536
	ds_read_b128 v[208:211], v10 offset:3072
	s_waitcnt lgkmcnt(12)
	v_pk_mul_f32 v[144:145], v[138:139], v[164:165]
	v_pk_fma_f32 v[144:145], v[140:141], v[166:167], v[144:145]
	v_add_f32 v146, v144, v145
	ds_read_b128 v[212:215], v10 offset:3328
	ds_read_b128 v[216:219], v10 offset:3584
	ds_read_b128 v[220:223], v10 offset:3840
	ds_read_b128 v[224:227], v10 offset:4096
	ds_read_b32 v228, v11 offset:3072
	ds_read_b128 v[230:233], v10 offset:4608
	v_add_f32_dpp v146, v146, v146 quad_perm:[1,0,3,2] row_mask:0xf bank_mask:0xf bound_ctrl:1
	s_nop 0
	s_nop 0
	v_add_f32_dpp v146, v146, v146 quad_perm:[2,3,0,1] row_mask:0xf bank_mask:0xf bound_ctrl:1
	s_waitcnt lgkmcnt(12)
	v_pk_mul_f32 v[176:177], v[176:177], v[184:185] op_sel_hi:[1,0]
	v_add_f32_dpp v146, v146, v146 row_half_mirror row_mask:0xf bank_mask:0xf bound_ctrl:1
	v_pk_mul_f32 v[178:179], v[178:179], v[184:185] op_sel_hi:[1,0]
	s_nop 0
	v_add_f32_dpp v146, v146, v146 row_mirror row_mask:0xf bank_mask:0xf bound_ctrl:1
	v_pk_fma_f32 v[176:177], v[146:147], v[168:169], v[176:177] op_sel_hi:[0,1,1] neg_lo:[1,0,0] neg_hi:[1,0,0]
	v_pk_fma_f32 v[178:179], v[146:147], v[170:171], v[178:179] op_sel_hi:[0,1,1] neg_lo:[1,0,0] neg_hi:[1,0,0]
	v_pk_fma_f32 v[138:139], v[138:139], v[172:173], v[176:177]
	v_pk_fma_f32 v[140:141], v[140:141], v[174:175], v[178:179]
	v_pk_mul_f32 v[144:145], v[138:139], v[186:187]
	v_pk_fma_f32 v[144:145], v[140:141], v[188:189], v[144:145]
	v_add_f32 v146, v144, v145
	ds_read_b128 v[234:237], v10 offset:4864
	ds_read_b128 v[238:241], v10 offset:5120
	ds_read_b128 v[242:245], v10 offset:5376
	ds_read_b128 v[246:249], v10 offset:5632
	ds_read_b32 v250, v11 offset:4608
	ds_read_b128 v[164:167], v10 offset:6144
	v_add_f32_dpp v146, v146, v146 quad_perm:[1,0,3,2] row_mask:0xf bank_mask:0xf bound_ctrl:1
	v_pk_mul_f32 v[180:181], v[138:139], v[180:181]
	v_pk_fma_f32 v[180:181], v[140:141], v[182:183], v[180:181]
	v_add_f32_dpp v146, v146, v146 quad_perm:[2,3,0,1] row_mask:0xf bank_mask:0xf bound_ctrl:1
	s_waitcnt lgkmcnt(12)
	v_pk_mul_f32 v[198:199], v[198:199], v[206:207] op_sel_hi:[1,0]
	v_add_f32_dpp v146, v146, v146 row_half_mirror row_mask:0xf bank_mask:0xf bound_ctrl:1
	v_pk_mul_f32 v[200:201], v[200:201], v[206:207] op_sel_hi:[1,0]
	v_add_f32 v148, v180, v181
	v_add_f32_dpp v146, v146, v146 row_mirror row_mask:0xf bank_mask:0xf bound_ctrl:1
	v_pk_fma_f32 v[198:199], v[146:147], v[190:191], v[198:199] op_sel_hi:[0,1,1] neg_lo:[1,0,0] neg_hi:[1,0,0]
	v_pk_fma_f32 v[200:201], v[146:147], v[192:193], v[200:201] op_sel_hi:[0,1,1] neg_lo:[1,0,0] neg_hi:[1,0,0]
	v_pk_fma_f32 v[138:139], v[138:139], v[194:195], v[198:199]
	v_pk_fma_f32 v[140:141], v[140:141], v[196:197], v[200:201]
	v_pk_mul_f32 v[144:145], v[138:139], v[208:209]
	v_pk_fma_f32 v[144:145], v[140:141], v[210:211], v[144:145]
	v_add_f32 v146, v144, v145
	ds_read_b128 v[168:171], v10 offset:6400
	ds_read_b128 v[172:175], v10 offset:6656
	ds_read_b128 v[176:179], v10 offset:6912
	ds_read_b128 v[180:183], v10 offset:7168
	ds_read_b32 v184, v11 offset:6144
	ds_read_b128 v[186:189], v10 offset:7680
	v_add_f32_dpp v146, v146, v146 quad_perm:[1,0,3,2] row_mask:0xf bank_mask:0xf bound_ctrl:1
	v_pk_mul_f32 v[202:203], v[138:139], v[202:203]
	v_pk_fma_f32 v[202:203], v[140:141], v[204:205], v[202:203]
	v_add_f32_dpp v146, v146, v146 quad_perm:[2,3,0,1] row_mask:0xf bank_mask:0xf bound_ctrl:1
	s_waitcnt lgkmcnt(12)
	v_pk_mul_f32 v[220:221], v[220:221], v[228:229] op_sel_hi:[1,0]
	v_add_f32_dpp v146, v146, v146 row_half_mirror row_mask:0xf bank_mask:0xf bound_ctrl:1
	v_pk_mul_f32 v[222:223], v[222:223], v[228:229] op_sel_hi:[1,0]
	v_add_f32 v149, v202, v203
	v_add_f32_dpp v146, v146, v146 row_mirror row_mask:0xf bank_mask:0xf bound_ctrl:1
	v_pk_fma_f32 v[220:221], v[146:147], v[212:213], v[220:221] op_sel_hi:[0,1,1] neg_lo:[1,0,0] neg_hi:[1,0,0]
	v_pk_fma_f32 v[222:223], v[146:147], v[214:215], v[222:223] op_sel_hi:[0,1,1] neg_lo:[1,0,0] neg_hi:[1,0,0]
	v_pk_fma_f32 v[138:139], v[138:139], v[216:217], v[220:221]
	v_pk_fma_f32 v[140:141], v[140:141], v[218:219], v[222:223]
	v_pk_mul_f32 v[144:145], v[138:139], v[230:231]
	v_pk_fma_f32 v[144:145], v[140:141], v[232:233], v[144:145]
	v_add_f32 v146, v144, v145
	ds_read_b128 v[190:193], v10 offset:7936
	ds_read_b128 v[194:197], v10 offset:8192
	ds_read_b128 v[198:201], v10 offset:8448
	ds_read_b128 v[202:205], v10 offset:8704
	ds_read_b32 v206, v11 offset:7680
	ds_read_b128 v[208:211], v10 offset:9216
	v_add_f32_dpp v146, v146, v146 quad_perm:[1,0,3,2] row_mask:0xf bank_mask:0xf bound_ctrl:1
	v_pk_mul_f32 v[224:225], v[138:139], v[224:225]
	v_pk_fma_f32 v[224:225], v[140:141], v[226:227], v[224:225]
	v_add_f32_dpp v146, v146, v146 quad_perm:[2,3,0,1] row_mask:0xf bank_mask:0xf bound_ctrl:1
	s_waitcnt lgkmcnt(12)
	v_pk_mul_f32 v[242:243], v[242:243], v[250:251] op_sel_hi:[1,0]
	v_add_f32_dpp v146, v146, v146 row_half_mirror row_mask:0xf bank_mask:0xf bound_ctrl:1
	v_pk_mul_f32 v[244:245], v[244:245], v[250:251] op_sel_hi:[1,0]
	v_add_f32 v150, v224, v225
	v_add_f32_dpp v146, v146, v146 row_mirror row_mask:0xf bank_mask:0xf bound_ctrl:1
	v_pk_fma_f32 v[242:243], v[146:147], v[234:235], v[242:243] op_sel_hi:[0,1,1] neg_lo:[1,0,0] neg_hi:[1,0,0]
	v_pk_fma_f32 v[244:245], v[146:147], v[236:237], v[244:245] op_sel_hi:[0,1,1] neg_lo:[1,0,0] neg_hi:[1,0,0]
	v_pk_fma_f32 v[138:139], v[138:139], v[238:239], v[242:243]
	v_pk_fma_f32 v[140:141], v[140:141], v[240:241], v[244:245]
	v_pk_mul_f32 v[144:145], v[138:139], v[164:165]
	v_pk_fma_f32 v[144:145], v[140:141], v[166:167], v[144:145]
	v_add_f32 v146, v144, v145
	ds_read_b128 v[212:215], v10 offset:9472
	ds_read_b128 v[216:219], v10 offset:9728
	ds_read_b128 v[220:223], v10 offset:9984
	ds_read_b128 v[224:227], v10 offset:10240
	ds_read_b32 v228, v11 offset:9216
	ds_read_b128 v[230:233], v10 offset:10752
	v_add_f32_dpp v146, v146, v146 quad_perm:[1,0,3,2] row_mask:0xf bank_mask:0xf bound_ctrl:1
	v_pk_mul_f32 v[246:247], v[138:139], v[246:247]
	v_pk_fma_f32 v[246:247], v[140:141], v[248:249], v[246:247]
	v_add_f32_dpp v146, v146, v146 quad_perm:[2,3,0,1] row_mask:0xf bank_mask:0xf bound_ctrl:1
	s_waitcnt lgkmcnt(12)
	v_pk_mul_f32 v[176:177], v[176:177], v[184:185] op_sel_hi:[1,0]
	v_add_f32_dpp v146, v146, v146 row_half_mirror row_mask:0xf bank_mask:0xf bound_ctrl:1
	v_pk_mul_f32 v[178:179], v[178:179], v[184:185] op_sel_hi:[1,0]
	v_add_f32 v151, v246, v247
	v_add_f32_dpp v146, v146, v146 row_mirror row_mask:0xf bank_mask:0xf bound_ctrl:1
	v_pk_fma_f32 v[176:177], v[146:147], v[168:169], v[176:177] op_sel_hi:[0,1,1] neg_lo:[1,0,0] neg_hi:[1,0,0]
	v_pk_fma_f32 v[178:179], v[146:147], v[170:171], v[178:179] op_sel_hi:[0,1,1] neg_lo:[1,0,0] neg_hi:[1,0,0]
	v_pk_fma_f32 v[138:139], v[138:139], v[172:173], v[176:177]
	v_pk_fma_f32 v[140:141], v[140:141], v[174:175], v[178:179]
	v_pk_mul_f32 v[144:145], v[138:139], v[186:187]
	v_pk_fma_f32 v[144:145], v[140:141], v[188:189], v[144:145]
	v_add_f32 v146, v144, v145
	ds_read_b128 v[234:237], v10 offset:11008
	ds_read_b128 v[238:241], v10 offset:11264
	ds_read_b128 v[242:245], v10 offset:11520
	ds_read_b128 v[246:249], v10 offset:11776
	ds_read_b32 v250, v11 offset:10752
	ds_read_b128 v[164:167], v10 offset:12288
	v_add_f32_dpp v146, v146, v146 quad_perm:[1,0,3,2] row_mask:0xf bank_mask:0xf bound_ctrl:1
	v_pk_mul_f32 v[180:181], v[138:139], v[180:181]
	v_pk_fma_f32 v[180:181], v[140:141], v[182:183], v[180:181]
	v_add_f32_dpp v146, v146, v146 quad_perm:[2,3,0,1] row_mask:0xf bank_mask:0xf bound_ctrl:1
	s_waitcnt lgkmcnt(12)
	v_pk_mul_f32 v[198:199], v[198:199], v[206:207] op_sel_hi:[1,0]
	v_add_f32_dpp v146, v146, v146 row_half_mirror row_mask:0xf bank_mask:0xf bound_ctrl:1
	v_pk_mul_f32 v[200:201], v[200:201], v[206:207] op_sel_hi:[1,0]
	v_add_f32 v152, v180, v181
	v_add_f32_dpp v146, v146, v146 row_mirror row_mask:0xf bank_mask:0xf bound_ctrl:1
	v_pk_fma_f32 v[198:199], v[146:147], v[190:191], v[198:199] op_sel_hi:[0,1,1] neg_lo:[1,0,0] neg_hi:[1,0,0]
	v_pk_fma_f32 v[200:201], v[146:147], v[192:193], v[200:201] op_sel_hi:[0,1,1] neg_lo:[1,0,0] neg_hi:[1,0,0]
	v_pk_fma_f32 v[138:139], v[138:139], v[194:195], v[198:199]
	v_pk_fma_f32 v[140:141], v[140:141], v[196:197], v[200:201]
	v_pk_mul_f32 v[144:145], v[138:139], v[208:209]
	v_pk_fma_f32 v[144:145], v[140:141], v[210:211], v[144:145]
	v_add_f32 v146, v144, v145
	ds_read_b128 v[168:171], v10 offset:12544
	ds_read_b128 v[172:175], v10 offset:12800
	ds_read_b128 v[176:179], v10 offset:13056
	ds_read_b128 v[180:183], v10 offset:13312
	ds_read_b32 v184, v11 offset:12288
	ds_read_b128 v[186:189], v10 offset:13824
	v_add_f32_dpp v146, v146, v146 quad_perm:[1,0,3,2] row_mask:0xf bank_mask:0xf bound_ctrl:1
	v_pk_mul_f32 v[202:203], v[138:139], v[202:203]
	v_pk_fma_f32 v[202:203], v[140:141], v[204:205], v[202:203]
	v_add_f32_dpp v146, v146, v146 quad_perm:[2,3,0,1] row_mask:0xf bank_mask:0xf bound_ctrl:1
	s_waitcnt lgkmcnt(12)
	v_pk_mul_f32 v[220:221], v[220:221], v[228:229] op_sel_hi:[1,0]
	v_add_f32_dpp v146, v146, v146 row_half_mirror row_mask:0xf bank_mask:0xf bound_ctrl:1
	v_pk_mul_f32 v[222:223], v[222:223], v[228:229] op_sel_hi:[1,0]
	v_add_f32 v153, v202, v203
	v_add_f32_dpp v146, v146, v146 row_mirror row_mask:0xf bank_mask:0xf bound_ctrl:1
	v_pk_fma_f32 v[220:221], v[146:147], v[212:213], v[220:221] op_sel_hi:[0,1,1] neg_lo:[1,0,0] neg_hi:[1,0,0]
	v_pk_fma_f32 v[222:223], v[146:147], v[214:215], v[222:223] op_sel_hi:[0,1,1] neg_lo:[1,0,0] neg_hi:[1,0,0]
	v_pk_fma_f32 v[138:139], v[138:139], v[216:217], v[220:221]
	v_pk_fma_f32 v[140:141], v[140:141], v[218:219], v[222:223]
	v_pk_mul_f32 v[144:145], v[138:139], v[230:231]
	v_pk_fma_f32 v[144:145], v[140:141], v[232:233], v[144:145]
	v_add_f32 v146, v144, v145
	ds_read_b128 v[190:193], v10 offset:14080
	ds_read_b128 v[194:197], v10 offset:14336
	ds_read_b128 v[198:201], v10 offset:14592
	ds_read_b128 v[202:205], v10 offset:14848
	ds_read_b32 v206, v11 offset:13824
	ds_read_b128 v[208:211], v10 offset:15360
	v_add_f32_dpp v146, v146, v146 quad_perm:[1,0,3,2] row_mask:0xf bank_mask:0xf bound_ctrl:1
	v_pk_mul_f32 v[224:225], v[138:139], v[224:225]
	v_pk_fma_f32 v[224:225], v[140:141], v[226:227], v[224:225]
	v_add_f32_dpp v146, v146, v146 quad_perm:[2,3,0,1] row_mask:0xf bank_mask:0xf bound_ctrl:1
	s_waitcnt lgkmcnt(12)
	v_pk_mul_f32 v[242:243], v[242:243], v[250:251] op_sel_hi:[1,0]
	v_add_f32_dpp v146, v146, v146 row_half_mirror row_mask:0xf bank_mask:0xf bound_ctrl:1
	v_pk_mul_f32 v[244:245], v[244:245], v[250:251] op_sel_hi:[1,0]
	v_add_f32 v154, v224, v225
	v_add_f32_dpp v146, v146, v146 row_mirror row_mask:0xf bank_mask:0xf bound_ctrl:1
	v_pk_fma_f32 v[242:243], v[146:147], v[234:235], v[242:243] op_sel_hi:[0,1,1] neg_lo:[1,0,0] neg_hi:[1,0,0]
	v_pk_fma_f32 v[244:245], v[146:147], v[236:237], v[244:245] op_sel_hi:[0,1,1] neg_lo:[1,0,0] neg_hi:[1,0,0]
	v_pk_fma_f32 v[138:139], v[138:139], v[238:239], v[242:243]
	v_pk_fma_f32 v[140:141], v[140:141], v[240:241], v[244:245]
	v_pk_mul_f32 v[144:145], v[138:139], v[164:165]
	v_pk_fma_f32 v[144:145], v[140:141], v[166:167], v[144:145]
	v_add_f32 v146, v144, v145
	ds_read_b128 v[212:215], v10 offset:15616
	ds_read_b128 v[216:219], v10 offset:15872
	ds_read_b128 v[220:223], v10 offset:16128
	ds_read_b128 v[224:227], v10 offset:16384
	ds_read_b32 v228, v11 offset:15360
	ds_read_b128 v[230:233], v10 offset:16896
	v_add_f32_dpp v146, v146, v146 quad_perm:[1,0,3,2] row_mask:0xf bank_mask:0xf bound_ctrl:1
	v_pk_mul_f32 v[246:247], v[138:139], v[246:247]
	v_pk_fma_f32 v[246:247], v[140:141], v[248:249], v[246:247]
	v_add_f32_dpp v146, v146, v146 quad_perm:[2,3,0,1] row_mask:0xf bank_mask:0xf bound_ctrl:1
	s_waitcnt lgkmcnt(12)
	v_pk_mul_f32 v[176:177], v[176:177], v[184:185] op_sel_hi:[1,0]
	v_add_f32_dpp v146, v146, v146 row_half_mirror row_mask:0xf bank_mask:0xf bound_ctrl:1
	v_pk_mul_f32 v[178:179], v[178:179], v[184:185] op_sel_hi:[1,0]
	v_add_f32 v155, v246, v247
	v_add_f32_dpp v146, v146, v146 row_mirror row_mask:0xf bank_mask:0xf bound_ctrl:1
	v_pk_fma_f32 v[176:177], v[146:147], v[168:169], v[176:177] op_sel_hi:[0,1,1] neg_lo:[1,0,0] neg_hi:[1,0,0]
	v_pk_fma_f32 v[178:179], v[146:147], v[170:171], v[178:179] op_sel_hi:[0,1,1] neg_lo:[1,0,0] neg_hi:[1,0,0]
	v_pk_fma_f32 v[138:139], v[138:139], v[172:173], v[176:177]
	v_pk_fma_f32 v[140:141], v[140:141], v[174:175], v[178:179]
	v_pk_mul_f32 v[144:145], v[138:139], v[186:187]
	v_pk_fma_f32 v[144:145], v[140:141], v[188:189], v[144:145]
	v_add_f32 v146, v144, v145
	ds_read_b128 v[234:237], v10 offset:17152
	ds_read_b128 v[238:241], v10 offset:17408
	ds_read_b128 v[242:245], v10 offset:17664
	ds_read_b128 v[246:249], v10 offset:17920
	ds_read_b32 v250, v11 offset:16896
	ds_read_b128 v[164:167], v10 offset:18432
	v_add_f32_dpp v146, v146, v146 quad_perm:[1,0,3,2] row_mask:0xf bank_mask:0xf bound_ctrl:1
	v_pk_mul_f32 v[180:181], v[138:139], v[180:181]
	v_pk_fma_f32 v[180:181], v[140:141], v[182:183], v[180:181]
	v_add_f32_dpp v146, v146, v146 quad_perm:[2,3,0,1] row_mask:0xf bank_mask:0xf bound_ctrl:1
	s_waitcnt lgkmcnt(12)
	v_pk_mul_f32 v[198:199], v[198:199], v[206:207] op_sel_hi:[1,0]
	v_add_f32_dpp v146, v146, v146 row_half_mirror row_mask:0xf bank_mask:0xf bound_ctrl:1
	v_pk_mul_f32 v[200:201], v[200:201], v[206:207] op_sel_hi:[1,0]
	v_add_f32 v156, v180, v181
	v_add_f32_dpp v146, v146, v146 row_mirror row_mask:0xf bank_mask:0xf bound_ctrl:1
	v_pk_fma_f32 v[198:199], v[146:147], v[190:191], v[198:199] op_sel_hi:[0,1,1] neg_lo:[1,0,0] neg_hi:[1,0,0]
	v_pk_fma_f32 v[200:201], v[146:147], v[192:193], v[200:201] op_sel_hi:[0,1,1] neg_lo:[1,0,0] neg_hi:[1,0,0]
	v_pk_fma_f32 v[138:139], v[138:139], v[194:195], v[198:199]
	v_pk_fma_f32 v[140:141], v[140:141], v[196:197], v[200:201]
	v_pk_mul_f32 v[144:145], v[138:139], v[208:209]
	v_pk_fma_f32 v[144:145], v[140:141], v[210:211], v[144:145]
	v_add_f32 v146, v144, v145
	ds_read_b128 v[168:171], v10 offset:18688
	ds_read_b128 v[172:175], v10 offset:18944
	ds_read_b128 v[176:179], v10 offset:19200
	ds_read_b128 v[180:183], v10 offset:19456
	ds_read_b32 v184, v11 offset:18432
	ds_read_b128 v[186:189], v10 offset:19968
	v_add_f32_dpp v146, v146, v146 quad_perm:[1,0,3,2] row_mask:0xf bank_mask:0xf bound_ctrl:1
	v_pk_mul_f32 v[202:203], v[138:139], v[202:203]
	v_pk_fma_f32 v[202:203], v[140:141], v[204:205], v[202:203]
	v_add_f32_dpp v146, v146, v146 quad_perm:[2,3,0,1] row_mask:0xf bank_mask:0xf bound_ctrl:1
	s_waitcnt lgkmcnt(12)
	v_pk_mul_f32 v[220:221], v[220:221], v[228:229] op_sel_hi:[1,0]
	v_add_f32_dpp v146, v146, v146 row_half_mirror row_mask:0xf bank_mask:0xf bound_ctrl:1
	v_pk_mul_f32 v[222:223], v[222:223], v[228:229] op_sel_hi:[1,0]
	v_add_f32 v157, v202, v203
	v_add_f32_dpp v146, v146, v146 row_mirror row_mask:0xf bank_mask:0xf bound_ctrl:1
	v_pk_fma_f32 v[220:221], v[146:147], v[212:213], v[220:221] op_sel_hi:[0,1,1] neg_lo:[1,0,0] neg_hi:[1,0,0]
	v_pk_fma_f32 v[222:223], v[146:147], v[214:215], v[222:223] op_sel_hi:[0,1,1] neg_lo:[1,0,0] neg_hi:[1,0,0]
	v_pk_fma_f32 v[138:139], v[138:139], v[216:217], v[220:221]
	v_pk_fma_f32 v[140:141], v[140:141], v[218:219], v[222:223]
	v_pk_mul_f32 v[144:145], v[138:139], v[230:231]
	v_pk_fma_f32 v[144:145], v[140:141], v[232:233], v[144:145]
	v_add_f32 v146, v144, v145
	ds_read_b128 v[190:193], v10 offset:20224
	ds_read_b128 v[194:197], v10 offset:20480
	ds_read_b128 v[198:201], v10 offset:20736
	ds_read_b128 v[202:205], v10 offset:20992
	ds_read_b32 v206, v11 offset:19968
	ds_read_b128 v[208:211], v10 offset:21504
	v_add_f32_dpp v146, v146, v146 quad_perm:[1,0,3,2] row_mask:0xf bank_mask:0xf bound_ctrl:1
	v_pk_mul_f32 v[224:225], v[138:139], v[224:225]
	v_pk_fma_f32 v[224:225], v[140:141], v[226:227], v[224:225]
	v_add_f32_dpp v146, v146, v146 quad_perm:[2,3,0,1] row_mask:0xf bank_mask:0xf bound_ctrl:1
	s_waitcnt lgkmcnt(12)
	v_pk_mul_f32 v[242:243], v[242:243], v[250:251] op_sel_hi:[1,0]
	v_add_f32_dpp v146, v146, v146 row_half_mirror row_mask:0xf bank_mask:0xf bound_ctrl:1
	v_pk_mul_f32 v[244:245], v[244:245], v[250:251] op_sel_hi:[1,0]
	v_add_f32 v158, v224, v225
	v_add_f32_dpp v146, v146, v146 row_mirror row_mask:0xf bank_mask:0xf bound_ctrl:1
	v_pk_fma_f32 v[242:243], v[146:147], v[234:235], v[242:243] op_sel_hi:[0,1,1] neg_lo:[1,0,0] neg_hi:[1,0,0]
	v_pk_fma_f32 v[244:245], v[146:147], v[236:237], v[244:245] op_sel_hi:[0,1,1] neg_lo:[1,0,0] neg_hi:[1,0,0]
	v_pk_fma_f32 v[138:139], v[138:139], v[238:239], v[242:243]
	v_pk_fma_f32 v[140:141], v[140:141], v[240:241], v[244:245]
	v_pk_mul_f32 v[144:145], v[138:139], v[164:165]
	v_pk_fma_f32 v[144:145], v[140:141], v[166:167], v[144:145]
	v_add_f32 v146, v144, v145
	ds_read_b128 v[212:215], v10 offset:21760
	ds_read_b128 v[216:219], v10 offset:22016
	ds_read_b128 v[220:223], v10 offset:22272
	ds_read_b128 v[224:227], v10 offset:22528
	ds_read_b32 v228, v11 offset:21504
	ds_read_b128 v[230:233], v10 offset:23040
	v_add_f32_dpp v146, v146, v146 quad_perm:[1,0,3,2] row_mask:0xf bank_mask:0xf bound_ctrl:1
	v_pk_mul_f32 v[246:247], v[138:139], v[246:247]
	v_pk_fma_f32 v[246:247], v[140:141], v[248:249], v[246:247]
	v_add_f32_dpp v146, v146, v146 quad_perm:[2,3,0,1] row_mask:0xf bank_mask:0xf bound_ctrl:1
	s_waitcnt lgkmcnt(12)
	v_pk_mul_f32 v[176:177], v[176:177], v[184:185] op_sel_hi:[1,0]
	v_add_f32_dpp v146, v146, v146 row_half_mirror row_mask:0xf bank_mask:0xf bound_ctrl:1
	v_pk_mul_f32 v[178:179], v[178:179], v[184:185] op_sel_hi:[1,0]
	v_add_f32 v159, v246, v247
	v_add_f32_dpp v146, v146, v146 row_mirror row_mask:0xf bank_mask:0xf bound_ctrl:1
	v_pk_fma_f32 v[176:177], v[146:147], v[168:169], v[176:177] op_sel_hi:[0,1,1] neg_lo:[1,0,0] neg_hi:[1,0,0]
	v_pk_fma_f32 v[178:179], v[146:147], v[170:171], v[178:179] op_sel_hi:[0,1,1] neg_lo:[1,0,0] neg_hi:[1,0,0]
	v_pk_fma_f32 v[138:139], v[138:139], v[172:173], v[176:177]
	v_pk_fma_f32 v[140:141], v[140:141], v[174:175], v[178:179]
	v_pk_mul_f32 v[144:145], v[138:139], v[186:187]
	v_pk_fma_f32 v[144:145], v[140:141], v[188:189], v[144:145]
	v_add_f32 v146, v144, v145
	ds_read_b128 v[234:237], v10 offset:23296
	ds_read_b128 v[238:241], v10 offset:23552
	ds_read_b128 v[242:245], v10 offset:23808
	ds_read_b128 v[246:249], v10 offset:24064
	ds_read_b32 v250, v11 offset:23040
	ds_read_b128 v[164:167], v10 offset:24576
	v_add_f32_dpp v146, v146, v146 quad_perm:[1,0,3,2] row_mask:0xf bank_mask:0xf bound_ctrl:1
	v_pk_mul_f32 v[180:181], v[138:139], v[180:181]
	v_pk_fma_f32 v[180:181], v[140:141], v[182:183], v[180:181]
	v_add_f32_dpp v146, v146, v146 quad_perm:[2,3,0,1] row_mask:0xf bank_mask:0xf bound_ctrl:1
	s_waitcnt lgkmcnt(12)
	v_pk_mul_f32 v[198:199], v[198:199], v[206:207] op_sel_hi:[1,0]
	v_add_f32_dpp v146, v146, v146 row_half_mirror row_mask:0xf bank_mask:0xf bound_ctrl:1
	v_pk_mul_f32 v[200:201], v[200:201], v[206:207] op_sel_hi:[1,0]
	v_add_f32 v160, v180, v181
	v_add_f32_dpp v146, v146, v146 row_mirror row_mask:0xf bank_mask:0xf bound_ctrl:1
	v_pk_fma_f32 v[198:199], v[146:147], v[190:191], v[198:199] op_sel_hi:[0,1,1] neg_lo:[1,0,0] neg_hi:[1,0,0]
	v_pk_fma_f32 v[200:201], v[146:147], v[192:193], v[200:201] op_sel_hi:[0,1,1] neg_lo:[1,0,0] neg_hi:[1,0,0]
	v_pk_fma_f32 v[138:139], v[138:139], v[194:195], v[198:199]
	v_pk_fma_f32 v[140:141], v[140:141], v[196:197], v[200:201]
	v_pk_mul_f32 v[144:145], v[138:139], v[208:209]
	v_pk_fma_f32 v[144:145], v[140:141], v[210:211], v[144:145]
	v_add_f32 v146, v144, v145
	ds_read_b128 v[168:171], v10 offset:24832
	ds_read_b128 v[172:175], v10 offset:25088
	ds_read_b128 v[176:179], v10 offset:25344
	ds_read_b128 v[180:183], v10 offset:25600
	ds_read_b32 v184, v11 offset:24576
	ds_read_b128 v[186:189], v10 offset:26112
	v_add_f32_dpp v146, v146, v146 quad_perm:[1,0,3,2] row_mask:0xf bank_mask:0xf bound_ctrl:1
	v_pk_mul_f32 v[202:203], v[138:139], v[202:203]
	v_pk_fma_f32 v[202:203], v[140:141], v[204:205], v[202:203]
	v_add_f32_dpp v146, v146, v146 quad_perm:[2,3,0,1] row_mask:0xf bank_mask:0xf bound_ctrl:1
	s_waitcnt lgkmcnt(12)
	v_pk_mul_f32 v[220:221], v[220:221], v[228:229] op_sel_hi:[1,0]
	v_add_f32_dpp v146, v146, v146 row_half_mirror row_mask:0xf bank_mask:0xf bound_ctrl:1
	v_pk_mul_f32 v[222:223], v[222:223], v[228:229] op_sel_hi:[1,0]
	v_add_f32 v161, v202, v203
	v_add_f32_dpp v146, v146, v146 row_mirror row_mask:0xf bank_mask:0xf bound_ctrl:1
	v_pk_fma_f32 v[220:221], v[146:147], v[212:213], v[220:221] op_sel_hi:[0,1,1] neg_lo:[1,0,0] neg_hi:[1,0,0]
	v_pk_fma_f32 v[222:223], v[146:147], v[214:215], v[222:223] op_sel_hi:[0,1,1] neg_lo:[1,0,0] neg_hi:[1,0,0]
	v_pk_fma_f32 v[138:139], v[138:139], v[216:217], v[220:221]
	v_pk_fma_f32 v[140:141], v[140:141], v[218:219], v[222:223]
	v_pk_mul_f32 v[144:145], v[138:139], v[230:231]
	v_pk_fma_f32 v[144:145], v[140:141], v[232:233], v[144:145]
	v_add_f32 v146, v144, v145
	ds_read_b128 v[190:193], v10 offset:26368
	ds_read_b128 v[194:197], v10 offset:26624
	ds_read_b128 v[198:201], v10 offset:26880
	ds_read_b128 v[202:205], v10 offset:27136
	ds_read_b32 v206, v11 offset:26112
	ds_read_b128 v[208:211], v10 offset:27648
	v_add_f32_dpp v146, v146, v146 quad_perm:[1,0,3,2] row_mask:0xf bank_mask:0xf bound_ctrl:1
	v_pk_mul_f32 v[224:225], v[138:139], v[224:225]
	v_pk_fma_f32 v[224:225], v[140:141], v[226:227], v[224:225]
	v_add_f32_dpp v146, v146, v146 quad_perm:[2,3,0,1] row_mask:0xf bank_mask:0xf bound_ctrl:1
	s_waitcnt lgkmcnt(12)
	v_pk_mul_f32 v[242:243], v[242:243], v[250:251] op_sel_hi:[1,0]
	v_add_f32_dpp v146, v146, v146 row_half_mirror row_mask:0xf bank_mask:0xf bound_ctrl:1
	v_pk_mul_f32 v[244:245], v[244:245], v[250:251] op_sel_hi:[1,0]
	v_add_f32 v162, v224, v225
	v_add_f32_dpp v146, v146, v146 row_mirror row_mask:0xf bank_mask:0xf bound_ctrl:1
	v_pk_fma_f32 v[242:243], v[146:147], v[234:235], v[242:243] op_sel_hi:[0,1,1] neg_lo:[1,0,0] neg_hi:[1,0,0]
	v_pk_fma_f32 v[244:245], v[146:147], v[236:237], v[244:245] op_sel_hi:[0,1,1] neg_lo:[1,0,0] neg_hi:[1,0,0]
	v_pk_fma_f32 v[138:139], v[138:139], v[238:239], v[242:243]
	v_pk_fma_f32 v[140:141], v[140:141], v[240:241], v[244:245]
	v_pk_mul_f32 v[144:145], v[138:139], v[164:165]
	v_pk_fma_f32 v[144:145], v[140:141], v[166:167], v[144:145]
	v_add_f32 v146, v144, v145
	ds_read_b128 v[212:215], v10 offset:27904
	ds_read_b128 v[216:219], v10 offset:28160
	ds_read_b128 v[220:223], v10 offset:28416
	ds_read_b128 v[224:227], v10 offset:28672
	ds_read_b32 v228, v11 offset:27648
	ds_read_b128 v[230:233], v10 offset:29184
	v_add_f32_dpp v146, v146, v146 quad_perm:[1,0,3,2] row_mask:0xf bank_mask:0xf bound_ctrl:1
	v_pk_mul_f32 v[246:247], v[138:139], v[246:247]
	v_pk_fma_f32 v[246:247], v[140:141], v[248:249], v[246:247]
	v_add_f32_dpp v146, v146, v146 quad_perm:[2,3,0,1] row_mask:0xf bank_mask:0xf bound_ctrl:1
	s_waitcnt lgkmcnt(12)
	v_pk_mul_f32 v[176:177], v[176:177], v[184:185] op_sel_hi:[1,0]
	v_add_f32_dpp v146, v146, v146 row_half_mirror row_mask:0xf bank_mask:0xf bound_ctrl:1
	v_pk_mul_f32 v[178:179], v[178:179], v[184:185] op_sel_hi:[1,0]
	v_add_f32 v163, v246, v247
	v_add_f32_dpp v146, v146, v146 row_mirror row_mask:0xf bank_mask:0xf bound_ctrl:1
	v_pk_fma_f32 v[176:177], v[146:147], v[168:169], v[176:177] op_sel_hi:[0,1,1] neg_lo:[1,0,0] neg_hi:[1,0,0]
	v_pk_fma_f32 v[178:179], v[146:147], v[170:171], v[178:179] op_sel_hi:[0,1,1] neg_lo:[1,0,0] neg_hi:[1,0,0]
	v_pk_fma_f32 v[138:139], v[138:139], v[172:173], v[176:177]
	v_pk_fma_f32 v[140:141], v[140:141], v[174:175], v[178:179]
	v_pk_mul_f32 v[144:145], v[138:139], v[186:187]
	v_pk_fma_f32 v[144:145], v[140:141], v[188:189], v[144:145]
	v_add_f32 v146, v144, v145
	v_add_f32_dpp v102, v148, v148 row_mirror row_mask:0xf bank_mask:0x3 bound_ctrl:1
	v_add_f32_dpp v102, v156, v156 row_mirror row_mask:0xf bank_mask:0xc bound_ctrl:1
	v_add_f32_dpp v103, v149, v149 row_mirror row_mask:0xf bank_mask:0x3 bound_ctrl:1
	v_add_f32_dpp v103, v157, v157 row_mirror row_mask:0xf bank_mask:0xc bound_ctrl:1
	v_add_f32_dpp v104, v150, v150 row_mirror row_mask:0xf bank_mask:0x3 bound_ctrl:1
	v_add_f32_dpp v104, v158, v158 row_mirror row_mask:0xf bank_mask:0xc bound_ctrl:1
	v_add_f32_dpp v105, v151, v151 row_mirror row_mask:0xf bank_mask:0x3 bound_ctrl:1
	v_add_f32_dpp v105, v159, v159 row_mirror row_mask:0xf bank_mask:0xc bound_ctrl:1
	v_add_f32_dpp v106, v152, v152 row_mirror row_mask:0xf bank_mask:0x3 bound_ctrl:1
	v_add_f32_dpp v106, v160, v160 row_mirror row_mask:0xf bank_mask:0xc bound_ctrl:1
	v_add_f32_dpp v107, v153, v153 row_mirror row_mask:0xf bank_mask:0x3 bound_ctrl:1
	v_add_f32_dpp v107, v161, v161 row_mirror row_mask:0xf bank_mask:0xc bound_ctrl:1
	v_add_f32_dpp v108, v154, v154 row_mirror row_mask:0xf bank_mask:0x3 bound_ctrl:1
	v_add_f32_dpp v108, v162, v162 row_mirror row_mask:0xf bank_mask:0xc bound_ctrl:1
	v_add_f32_dpp v109, v155, v155 row_mirror row_mask:0xf bank_mask:0x3 bound_ctrl:1
	v_add_f32_dpp v109, v163, v163 row_mirror row_mask:0xf bank_mask:0xc bound_ctrl:1
	v_add_f32_dpp v110, v102, v102 row_half_mirror row_mask:0xf bank_mask:0x5 bound_ctrl:1
	v_add_f32_dpp v110, v106, v106 row_half_mirror row_mask:0xf bank_mask:0xa bound_ctrl:1
	v_add_f32_dpp v111, v103, v103 row_half_mirror row_mask:0xf bank_mask:0x5 bound_ctrl:1
	v_add_f32_dpp v111, v107, v107 row_half_mirror row_mask:0xf bank_mask:0xa bound_ctrl:1
	v_add_f32_dpp v112, v104, v104 row_half_mirror row_mask:0xf bank_mask:0x5 bound_ctrl:1
	v_add_f32_dpp v112, v108, v108 row_half_mirror row_mask:0xf bank_mask:0xa bound_ctrl:1
	v_add_f32_dpp v113, v105, v105 row_half_mirror row_mask:0xf bank_mask:0x5 bound_ctrl:1
	v_add_f32_dpp v113, v109, v109 row_half_mirror row_mask:0xf bank_mask:0xa bound_ctrl:1
	s_mov_b32 vcc_lo, 0xcccccccc
	s_mov_b32 vcc_hi, 0xcccccccc
	v_cndmask_b32 v116, v112, v110, vcc
	v_cndmask_b32 v117, v113, v111, vcc
	v_cndmask_b32 v114, v110, v112, vcc
	v_cndmask_b32 v115, v111, v113, vcc
	v_add_f32_dpp v114, v116, v114 quad_perm:[2,3,0,1] row_mask:0xf bank_mask:0xf bound_ctrl:1
	v_add_f32_dpp v115, v117, v115 quad_perm:[2,3,0,1] row_mask:0xf bank_mask:0xf bound_ctrl:1
	s_mov_b32 vcc_lo, 0xaaaaaaaa
	s_mov_b32 vcc_hi, 0xaaaaaaaa
	v_cndmask_b32 v116, v115, v114, vcc
	v_cndmask_b32 v117, v114, v115, vcc
	s_nop 0
	v_add_f32_dpp v18, v116, v117 quad_perm:[1,0,3,2] row_mask:0xf bank_mask:0xf bound_ctrl:1
	ds_read_b128 v[234:237], v10 offset:29440
	ds_read_b128 v[238:241], v10 offset:29696
	ds_read_b128 v[242:245], v10 offset:29952
	ds_read_b128 v[246:249], v10 offset:30208
	ds_read_b32 v250, v11 offset:29184
	ds_read_b128 v[164:167], v10 offset:30720
	v_add_f32_dpp v146, v146, v146 quad_perm:[1,0,3,2] row_mask:0xf bank_mask:0xf bound_ctrl:1
	v_pk_mul_f32 v[180:181], v[138:139], v[180:181]
	v_pk_fma_f32 v[180:181], v[140:141], v[182:183], v[180:181]
	v_add_f32_dpp v146, v146, v146 quad_perm:[2,3,0,1] row_mask:0xf bank_mask:0xf bound_ctrl:1
	s_waitcnt lgkmcnt(12)
	v_pk_mul_f32 v[198:199], v[198:199], v[206:207] op_sel_hi:[1,0]
	v_add_f32_dpp v146, v146, v146 row_half_mirror row_mask:0xf bank_mask:0xf bound_ctrl:1
	v_pk_mul_f32 v[200:201], v[200:201], v[206:207] op_sel_hi:[1,0]
	v_add_f32 v148, v180, v181
	v_add_f32_dpp v146, v146, v146 row_mirror row_mask:0xf bank_mask:0xf bound_ctrl:1
	v_pk_fma_f32 v[198:199], v[146:147], v[190:191], v[198:199] op_sel_hi:[0,1,1] neg_lo:[1,0,0] neg_hi:[1,0,0]
	v_pk_fma_f32 v[200:201], v[146:147], v[192:193], v[200:201] op_sel_hi:[0,1,1] neg_lo:[1,0,0] neg_hi:[1,0,0]
	v_pk_fma_f32 v[138:139], v[138:139], v[194:195], v[198:199]
	v_pk_fma_f32 v[140:141], v[140:141], v[196:197], v[200:201]
	v_pk_mul_f32 v[144:145], v[138:139], v[208:209]
	v_pk_fma_f32 v[144:145], v[140:141], v[210:211], v[144:145]
	v_add_f32 v146, v144, v145
	ds_read_b128 v[168:171], v10 offset:30976
	ds_read_b128 v[172:175], v10 offset:31232
	ds_read_b128 v[176:179], v10 offset:31488
	ds_read_b128 v[180:183], v10 offset:31744
	ds_read_b32 v184, v11 offset:30720
	ds_read_b128 v[186:189], v10 offset:32256
	v_add_f32_dpp v146, v146, v146 quad_perm:[1,0,3,2] row_mask:0xf bank_mask:0xf bound_ctrl:1
	v_pk_mul_f32 v[202:203], v[138:139], v[202:203]
	v_pk_fma_f32 v[202:203], v[140:141], v[204:205], v[202:203]
	v_add_f32_dpp v146, v146, v146 quad_perm:[2,3,0,1] row_mask:0xf bank_mask:0xf bound_ctrl:1
	s_waitcnt lgkmcnt(12)
	v_pk_mul_f32 v[220:221], v[220:221], v[228:229] op_sel_hi:[1,0]
	v_add_f32_dpp v146, v146, v146 row_half_mirror row_mask:0xf bank_mask:0xf bound_ctrl:1
	v_pk_mul_f32 v[222:223], v[222:223], v[228:229] op_sel_hi:[1,0]
	v_add_f32 v149, v202, v203
	v_add_f32_dpp v146, v146, v146 row_mirror row_mask:0xf bank_mask:0xf bound_ctrl:1
	v_pk_fma_f32 v[220:221], v[146:147], v[212:213], v[220:221] op_sel_hi:[0,1,1] neg_lo:[1,0,0] neg_hi:[1,0,0]
	v_pk_fma_f32 v[222:223], v[146:147], v[214:215], v[222:223] op_sel_hi:[0,1,1] neg_lo:[1,0,0] neg_hi:[1,0,0]
	v_pk_fma_f32 v[138:139], v[138:139], v[216:217], v[220:221]
	v_pk_fma_f32 v[140:141], v[140:141], v[218:219], v[222:223]
	v_pk_mul_f32 v[144:145], v[138:139], v[230:231]
	v_pk_fma_f32 v[144:145], v[140:141], v[232:233], v[144:145]
	v_add_f32 v146, v144, v145
	ds_read_b128 v[190:193], v10 offset:32512
	ds_read_b128 v[194:197], v10 offset:32768
	ds_read_b128 v[198:201], v10 offset:33024
	ds_read_b128 v[202:205], v10 offset:33280
	ds_read_b32 v206, v11 offset:32256
	ds_read_b128 v[208:211], v10 offset:33792
	v_add_f32_dpp v146, v146, v146 quad_perm:[1,0,3,2] row_mask:0xf bank_mask:0xf bound_ctrl:1
	v_pk_mul_f32 v[224:225], v[138:139], v[224:225]
	v_pk_fma_f32 v[224:225], v[140:141], v[226:227], v[224:225]
	v_add_f32_dpp v146, v146, v146 quad_perm:[2,3,0,1] row_mask:0xf bank_mask:0xf bound_ctrl:1
	s_waitcnt lgkmcnt(12)
	v_pk_mul_f32 v[242:243], v[242:243], v[250:251] op_sel_hi:[1,0]
	v_add_f32_dpp v146, v146, v146 row_half_mirror row_mask:0xf bank_mask:0xf bound_ctrl:1
	v_pk_mul_f32 v[244:245], v[244:245], v[250:251] op_sel_hi:[1,0]
	v_add_f32 v150, v224, v225
	v_add_f32_dpp v146, v146, v146 row_mirror row_mask:0xf bank_mask:0xf bound_ctrl:1
	v_pk_fma_f32 v[242:243], v[146:147], v[234:235], v[242:243] op_sel_hi:[0,1,1] neg_lo:[1,0,0] neg_hi:[1,0,0]
	v_pk_fma_f32 v[244:245], v[146:147], v[236:237], v[244:245] op_sel_hi:[0,1,1] neg_lo:[1,0,0] neg_hi:[1,0,0]
	v_pk_fma_f32 v[138:139], v[138:139], v[238:239], v[242:243]
	v_pk_fma_f32 v[140:141], v[140:141], v[240:241], v[244:245]
	v_pk_mul_f32 v[144:145], v[138:139], v[164:165]
	v_pk_fma_f32 v[144:145], v[140:141], v[166:167], v[144:145]
	v_add_f32 v146, v144, v145
	ds_read_b128 v[212:215], v10 offset:34048
	ds_read_b128 v[216:219], v10 offset:34304
	ds_read_b128 v[220:223], v10 offset:34560
	ds_read_b128 v[224:227], v10 offset:34816
	ds_read_b32 v228, v11 offset:33792
	ds_read_b128 v[230:233], v10 offset:35328
	v_add_f32_dpp v146, v146, v146 quad_perm:[1,0,3,2] row_mask:0xf bank_mask:0xf bound_ctrl:1
	v_pk_mul_f32 v[246:247], v[138:139], v[246:247]
	v_pk_fma_f32 v[246:247], v[140:141], v[248:249], v[246:247]
	v_add_f32_dpp v146, v146, v146 quad_perm:[2,3,0,1] row_mask:0xf bank_mask:0xf bound_ctrl:1
	s_waitcnt lgkmcnt(12)
	v_pk_mul_f32 v[176:177], v[176:177], v[184:185] op_sel_hi:[1,0]
	v_add_f32_dpp v146, v146, v146 row_half_mirror row_mask:0xf bank_mask:0xf bound_ctrl:1
	v_pk_mul_f32 v[178:179], v[178:179], v[184:185] op_sel_hi:[1,0]
	v_add_f32 v151, v246, v247
	v_add_f32_dpp v146, v146, v146 row_mirror row_mask:0xf bank_mask:0xf bound_ctrl:1
	v_pk_fma_f32 v[176:177], v[146:147], v[168:169], v[176:177] op_sel_hi:[0,1,1] neg_lo:[1,0,0] neg_hi:[1,0,0]
	v_pk_fma_f32 v[178:179], v[146:147], v[170:171], v[178:179] op_sel_hi:[0,1,1] neg_lo:[1,0,0] neg_hi:[1,0,0]
	v_pk_fma_f32 v[138:139], v[138:139], v[172:173], v[176:177]
	v_pk_fma_f32 v[140:141], v[140:141], v[174:175], v[178:179]
	v_pk_mul_f32 v[144:145], v[138:139], v[186:187]
	v_pk_fma_f32 v[144:145], v[140:141], v[188:189], v[144:145]
	v_add_f32 v146, v144, v145
	ds_read_b128 v[234:237], v10 offset:35584
	ds_read_b128 v[238:241], v10 offset:35840
	ds_read_b128 v[242:245], v10 offset:36096
	ds_read_b128 v[246:249], v10 offset:36352
	ds_read_b32 v250, v11 offset:35328
	ds_read_b128 v[164:167], v10 offset:36864
	v_add_f32_dpp v146, v146, v146 quad_perm:[1,0,3,2] row_mask:0xf bank_mask:0xf bound_ctrl:1
	v_pk_mul_f32 v[180:181], v[138:139], v[180:181]
	v_pk_fma_f32 v[180:181], v[140:141], v[182:183], v[180:181]
	v_add_f32_dpp v146, v146, v146 quad_perm:[2,3,0,1] row_mask:0xf bank_mask:0xf bound_ctrl:1
	s_waitcnt lgkmcnt(12)
	v_pk_mul_f32 v[198:199], v[198:199], v[206:207] op_sel_hi:[1,0]
	v_add_f32_dpp v146, v146, v146 row_half_mirror row_mask:0xf bank_mask:0xf bound_ctrl:1
	v_pk_mul_f32 v[200:201], v[200:201], v[206:207] op_sel_hi:[1,0]
	v_add_f32 v152, v180, v181
	v_add_f32_dpp v146, v146, v146 row_mirror row_mask:0xf bank_mask:0xf bound_ctrl:1
	v_pk_fma_f32 v[198:199], v[146:147], v[190:191], v[198:199] op_sel_hi:[0,1,1] neg_lo:[1,0,0] neg_hi:[1,0,0]
	v_pk_fma_f32 v[200:201], v[146:147], v[192:193], v[200:201] op_sel_hi:[0,1,1] neg_lo:[1,0,0] neg_hi:[1,0,0]
	v_pk_fma_f32 v[138:139], v[138:139], v[194:195], v[198:199]
	v_pk_fma_f32 v[140:141], v[140:141], v[196:197], v[200:201]
	v_pk_mul_f32 v[144:145], v[138:139], v[208:209]
	v_pk_fma_f32 v[144:145], v[140:141], v[210:211], v[144:145]
	v_add_f32 v146, v144, v145
	ds_read_b128 v[168:171], v10 offset:37120
	ds_read_b128 v[172:175], v10 offset:37376
	ds_read_b128 v[176:179], v10 offset:37632
	ds_read_b128 v[180:183], v10 offset:37888
	ds_read_b32 v184, v11 offset:36864
	ds_read_b128 v[186:189], v10 offset:38400
	v_add_f32_dpp v146, v146, v146 quad_perm:[1,0,3,2] row_mask:0xf bank_mask:0xf bound_ctrl:1
	v_pk_mul_f32 v[202:203], v[138:139], v[202:203]
	v_pk_fma_f32 v[202:203], v[140:141], v[204:205], v[202:203]
	v_add_f32_dpp v146, v146, v146 quad_perm:[2,3,0,1] row_mask:0xf bank_mask:0xf bound_ctrl:1
	s_waitcnt lgkmcnt(12)
	v_pk_mul_f32 v[220:221], v[220:221], v[228:229] op_sel_hi:[1,0]
	v_add_f32_dpp v146, v146, v146 row_half_mirror row_mask:0xf bank_mask:0xf bound_ctrl:1
	v_pk_mul_f32 v[222:223], v[222:223], v[228:229] op_sel_hi:[1,0]
	v_add_f32 v153, v202, v203
	v_add_f32_dpp v146, v146, v146 row_mirror row_mask:0xf bank_mask:0xf bound_ctrl:1
	v_pk_fma_f32 v[220:221], v[146:147], v[212:213], v[220:221] op_sel_hi:[0,1,1] neg_lo:[1,0,0] neg_hi:[1,0,0]
	v_pk_fma_f32 v[222:223], v[146:147], v[214:215], v[222:223] op_sel_hi:[0,1,1] neg_lo:[1,0,0] neg_hi:[1,0,0]
	v_pk_fma_f32 v[138:139], v[138:139], v[216:217], v[220:221]
	v_pk_fma_f32 v[140:141], v[140:141], v[218:219], v[222:223]
	v_pk_mul_f32 v[144:145], v[138:139], v[230:231]
	v_pk_fma_f32 v[144:145], v[140:141], v[232:233], v[144:145]
	v_add_f32 v146, v144, v145
	ds_read_b128 v[190:193], v10 offset:38656
	ds_read_b128 v[194:197], v10 offset:38912
	ds_read_b128 v[198:201], v10 offset:39168
	ds_read_b128 v[202:205], v10 offset:39424
	ds_read_b32 v206, v11 offset:38400
	ds_read_b128 v[208:211], v10 offset:39936
	v_add_f32_dpp v146, v146, v146 quad_perm:[1,0,3,2] row_mask:0xf bank_mask:0xf bound_ctrl:1
	v_pk_mul_f32 v[224:225], v[138:139], v[224:225]
	v_pk_fma_f32 v[224:225], v[140:141], v[226:227], v[224:225]
	v_add_f32_dpp v146, v146, v146 quad_perm:[2,3,0,1] row_mask:0xf bank_mask:0xf bound_ctrl:1
	s_waitcnt lgkmcnt(12)
	v_pk_mul_f32 v[242:243], v[242:243], v[250:251] op_sel_hi:[1,0]
	v_add_f32_dpp v146, v146, v146 row_half_mirror row_mask:0xf bank_mask:0xf bound_ctrl:1
	v_pk_mul_f32 v[244:245], v[244:245], v[250:251] op_sel_hi:[1,0]
	v_add_f32 v154, v224, v225
	v_add_f32_dpp v146, v146, v146 row_mirror row_mask:0xf bank_mask:0xf bound_ctrl:1
	v_pk_fma_f32 v[242:243], v[146:147], v[234:235], v[242:243] op_sel_hi:[0,1,1] neg_lo:[1,0,0] neg_hi:[1,0,0]
	v_pk_fma_f32 v[244:245], v[146:147], v[236:237], v[244:245] op_sel_hi:[0,1,1] neg_lo:[1,0,0] neg_hi:[1,0,0]
	v_pk_fma_f32 v[138:139], v[138:139], v[238:239], v[242:243]
	v_pk_fma_f32 v[140:141], v[140:141], v[240:241], v[244:245]
	v_pk_mul_f32 v[144:145], v[138:139], v[164:165]
	v_pk_fma_f32 v[144:145], v[140:141], v[166:167], v[144:145]
	v_add_f32 v146, v144, v145
	ds_read_b128 v[212:215], v10 offset:40192
	ds_read_b128 v[216:219], v10 offset:40448
	ds_read_b128 v[220:223], v10 offset:40704
	ds_read_b128 v[224:227], v10 offset:40960
	ds_read_b32 v228, v11 offset:39936
	ds_read_b128 v[230:233], v10 offset:41472
	v_add_f32_dpp v146, v146, v146 quad_perm:[1,0,3,2] row_mask:0xf bank_mask:0xf bound_ctrl:1
	v_pk_mul_f32 v[246:247], v[138:139], v[246:247]
	v_pk_fma_f32 v[246:247], v[140:141], v[248:249], v[246:247]
	v_add_f32_dpp v146, v146, v146 quad_perm:[2,3,0,1] row_mask:0xf bank_mask:0xf bound_ctrl:1
	s_waitcnt lgkmcnt(12)
	v_pk_mul_f32 v[176:177], v[176:177], v[184:185] op_sel_hi:[1,0]
	v_add_f32_dpp v146, v146, v146 row_half_mirror row_mask:0xf bank_mask:0xf bound_ctrl:1
	v_pk_mul_f32 v[178:179], v[178:179], v[184:185] op_sel_hi:[1,0]
	v_add_f32 v155, v246, v247
	v_add_f32_dpp v146, v146, v146 row_mirror row_mask:0xf bank_mask:0xf bound_ctrl:1
	v_pk_fma_f32 v[176:177], v[146:147], v[168:169], v[176:177] op_sel_hi:[0,1,1] neg_lo:[1,0,0] neg_hi:[1,0,0]
	v_pk_fma_f32 v[178:179], v[146:147], v[170:171], v[178:179] op_sel_hi:[0,1,1] neg_lo:[1,0,0] neg_hi:[1,0,0]
	v_pk_fma_f32 v[138:139], v[138:139], v[172:173], v[176:177]
	v_pk_fma_f32 v[140:141], v[140:141], v[174:175], v[178:179]
	v_pk_mul_f32 v[144:145], v[138:139], v[186:187]
	v_pk_fma_f32 v[144:145], v[140:141], v[188:189], v[144:145]
	v_add_f32 v146, v144, v145
	ds_read_b128 v[234:237], v10 offset:41728
	ds_read_b128 v[238:241], v10 offset:41984
	ds_read_b128 v[242:245], v10 offset:42240
	ds_read_b128 v[246:249], v10 offset:42496
	ds_read_b32 v250, v11 offset:41472
	ds_read_b128 v[164:167], v10 offset:43008
	v_add_f32_dpp v146, v146, v146 quad_perm:[1,0,3,2] row_mask:0xf bank_mask:0xf bound_ctrl:1
	v_pk_mul_f32 v[180:181], v[138:139], v[180:181]
	v_pk_fma_f32 v[180:181], v[140:141], v[182:183], v[180:181]
	v_add_f32_dpp v146, v146, v146 quad_perm:[2,3,0,1] row_mask:0xf bank_mask:0xf bound_ctrl:1
	s_waitcnt lgkmcnt(12)
	v_pk_mul_f32 v[198:199], v[198:199], v[206:207] op_sel_hi:[1,0]
	v_add_f32_dpp v146, v146, v146 row_half_mirror row_mask:0xf bank_mask:0xf bound_ctrl:1
	v_pk_mul_f32 v[200:201], v[200:201], v[206:207] op_sel_hi:[1,0]
	v_add_f32 v156, v180, v181
	v_add_f32_dpp v146, v146, v146 row_mirror row_mask:0xf bank_mask:0xf bound_ctrl:1
	v_pk_fma_f32 v[198:199], v[146:147], v[190:191], v[198:199] op_sel_hi:[0,1,1] neg_lo:[1,0,0] neg_hi:[1,0,0]
	v_pk_fma_f32 v[200:201], v[146:147], v[192:193], v[200:201] op_sel_hi:[0,1,1] neg_lo:[1,0,0] neg_hi:[1,0,0]
	v_pk_fma_f32 v[138:139], v[138:139], v[194:195], v[198:199]
	v_pk_fma_f32 v[140:141], v[140:141], v[196:197], v[200:201]
	v_pk_mul_f32 v[144:145], v[138:139], v[208:209]
	v_pk_fma_f32 v[144:145], v[140:141], v[210:211], v[144:145]
	v_add_f32 v146, v144, v145
	ds_read_b128 v[168:171], v10 offset:43264
	ds_read_b128 v[172:175], v10 offset:43520
	ds_read_b128 v[176:179], v10 offset:43776
	ds_read_b128 v[180:183], v10 offset:44032
	ds_read_b32 v184, v11 offset:43008
	ds_read_b128 v[186:189], v10 offset:44544
	v_add_f32_dpp v146, v146, v146 quad_perm:[1,0,3,2] row_mask:0xf bank_mask:0xf bound_ctrl:1
	v_pk_mul_f32 v[202:203], v[138:139], v[202:203]
	v_pk_fma_f32 v[202:203], v[140:141], v[204:205], v[202:203]
	v_add_f32_dpp v146, v146, v146 quad_perm:[2,3,0,1] row_mask:0xf bank_mask:0xf bound_ctrl:1
	s_waitcnt lgkmcnt(12)
	v_pk_mul_f32 v[220:221], v[220:221], v[228:229] op_sel_hi:[1,0]
	v_add_f32_dpp v146, v146, v146 row_half_mirror row_mask:0xf bank_mask:0xf bound_ctrl:1
	v_pk_mul_f32 v[222:223], v[222:223], v[228:229] op_sel_hi:[1,0]
	v_add_f32 v157, v202, v203
	v_add_f32_dpp v146, v146, v146 row_mirror row_mask:0xf bank_mask:0xf bound_ctrl:1
	v_pk_fma_f32 v[220:221], v[146:147], v[212:213], v[220:221] op_sel_hi:[0,1,1] neg_lo:[1,0,0] neg_hi:[1,0,0]
	v_pk_fma_f32 v[222:223], v[146:147], v[214:215], v[222:223] op_sel_hi:[0,1,1] neg_lo:[1,0,0] neg_hi:[1,0,0]
	v_pk_fma_f32 v[138:139], v[138:139], v[216:217], v[220:221]
	v_pk_fma_f32 v[140:141], v[140:141], v[218:219], v[222:223]
	v_pk_mul_f32 v[144:145], v[138:139], v[230:231]
	v_pk_fma_f32 v[144:145], v[140:141], v[232:233], v[144:145]
	v_add_f32 v146, v144, v145
	ds_read_b128 v[190:193], v10 offset:44800
	ds_read_b128 v[194:197], v10 offset:45056
	ds_read_b128 v[198:201], v10 offset:45312
	ds_read_b128 v[202:205], v10 offset:45568
	ds_read_b32 v206, v11 offset:44544
	ds_read_b128 v[208:211], v10 offset:46080
	v_add_f32_dpp v146, v146, v146 quad_perm:[1,0,3,2] row_mask:0xf bank_mask:0xf bound_ctrl:1
	v_pk_mul_f32 v[224:225], v[138:139], v[224:225]
	v_pk_fma_f32 v[224:225], v[140:141], v[226:227], v[224:225]
	v_add_f32_dpp v146, v146, v146 quad_perm:[2,3,0,1] row_mask:0xf bank_mask:0xf bound_ctrl:1
	s_waitcnt lgkmcnt(12)
	v_pk_mul_f32 v[242:243], v[242:243], v[250:251] op_sel_hi:[1,0]
	v_add_f32_dpp v146, v146, v146 row_half_mirror row_mask:0xf bank_mask:0xf bound_ctrl:1
	v_pk_mul_f32 v[244:245], v[244:245], v[250:251] op_sel_hi:[1,0]
	v_add_f32 v158, v224, v225
	v_add_f32_dpp v146, v146, v146 row_mirror row_mask:0xf bank_mask:0xf bound_ctrl:1
	v_pk_fma_f32 v[242:243], v[146:147], v[234:235], v[242:243] op_sel_hi:[0,1,1] neg_lo:[1,0,0] neg_hi:[1,0,0]
	v_pk_fma_f32 v[244:245], v[146:147], v[236:237], v[244:245] op_sel_hi:[0,1,1] neg_lo:[1,0,0] neg_hi:[1,0,0]
	v_pk_fma_f32 v[138:139], v[138:139], v[238:239], v[242:243]
	v_pk_fma_f32 v[140:141], v[140:141], v[240:241], v[244:245]
	v_pk_mul_f32 v[144:145], v[138:139], v[164:165]
	v_pk_fma_f32 v[144:145], v[140:141], v[166:167], v[144:145]
	v_add_f32 v146, v144, v145
	ds_read_b128 v[212:215], v10 offset:46336
	ds_read_b128 v[216:219], v10 offset:46592
	ds_read_b128 v[220:223], v10 offset:46848
	ds_read_b128 v[224:227], v10 offset:47104
	ds_read_b32 v228, v11 offset:46080
	ds_read_b128 v[230:233], v10 offset:47616
	v_add_f32_dpp v146, v146, v146 quad_perm:[1,0,3,2] row_mask:0xf bank_mask:0xf bound_ctrl:1
	v_pk_mul_f32 v[246:247], v[138:139], v[246:247]
	v_pk_fma_f32 v[246:247], v[140:141], v[248:249], v[246:247]
	v_add_f32_dpp v146, v146, v146 quad_perm:[2,3,0,1] row_mask:0xf bank_mask:0xf bound_ctrl:1
	s_waitcnt lgkmcnt(12)
	v_pk_mul_f32 v[176:177], v[176:177], v[184:185] op_sel_hi:[1,0]
	v_add_f32_dpp v146, v146, v146 row_half_mirror row_mask:0xf bank_mask:0xf bound_ctrl:1
	v_pk_mul_f32 v[178:179], v[178:179], v[184:185] op_sel_hi:[1,0]
	v_add_f32 v159, v246, v247
	v_add_f32_dpp v146, v146, v146 row_mirror row_mask:0xf bank_mask:0xf bound_ctrl:1
	v_pk_fma_f32 v[176:177], v[146:147], v[168:169], v[176:177] op_sel_hi:[0,1,1] neg_lo:[1,0,0] neg_hi:[1,0,0]
	v_pk_fma_f32 v[178:179], v[146:147], v[170:171], v[178:179] op_sel_hi:[0,1,1] neg_lo:[1,0,0] neg_hi:[1,0,0]
	v_pk_fma_f32 v[138:139], v[138:139], v[172:173], v[176:177]
	v_pk_fma_f32 v[140:141], v[140:141], v[174:175], v[178:179]
	v_pk_mul_f32 v[144:145], v[138:139], v[186:187]
	v_pk_fma_f32 v[144:145], v[140:141], v[188:189], v[144:145]
	v_add_f32 v146, v144, v145
	ds_read_b128 v[234:237], v10 offset:47872
	ds_read_b128 v[238:241], v10 offset:48128
	ds_read_b128 v[242:245], v10 offset:48384
	ds_read_b128 v[246:249], v10 offset:48640
	ds_read_b32 v250, v11 offset:47616
	v_add_f32_dpp v146, v146, v146 quad_perm:[1,0,3,2] row_mask:0xf bank_mask:0xf bound_ctrl:1
	v_pk_mul_f32 v[180:181], v[138:139], v[180:181]
	v_pk_fma_f32 v[180:181], v[140:141], v[182:183], v[180:181]
	v_add_f32_dpp v146, v146, v146 quad_perm:[2,3,0,1] row_mask:0xf bank_mask:0xf bound_ctrl:1
	s_waitcnt lgkmcnt(11)
	v_pk_mul_f32 v[198:199], v[198:199], v[206:207] op_sel_hi:[1,0]
	v_add_f32_dpp v146, v146, v146 row_half_mirror row_mask:0xf bank_mask:0xf bound_ctrl:1
	v_pk_mul_f32 v[200:201], v[200:201], v[206:207] op_sel_hi:[1,0]
	v_add_f32 v160, v180, v181
	v_add_f32_dpp v146, v146, v146 row_mirror row_mask:0xf bank_mask:0xf bound_ctrl:1
	v_pk_fma_f32 v[198:199], v[146:147], v[190:191], v[198:199] op_sel_hi:[0,1,1] neg_lo:[1,0,0] neg_hi:[1,0,0]
	v_pk_fma_f32 v[200:201], v[146:147], v[192:193], v[200:201] op_sel_hi:[0,1,1] neg_lo:[1,0,0] neg_hi:[1,0,0]
	v_pk_fma_f32 v[138:139], v[138:139], v[194:195], v[198:199]
	v_pk_fma_f32 v[140:141], v[140:141], v[196:197], v[200:201]
	v_pk_mul_f32 v[144:145], v[138:139], v[208:209]
	v_pk_fma_f32 v[144:145], v[140:141], v[210:211], v[144:145]
	v_add_f32 v146, v144, v145
	s_nop 1
	v_add_f32_dpp v146, v146, v146 quad_perm:[1,0,3,2] row_mask:0xf bank_mask:0xf bound_ctrl:1
	v_pk_mul_f32 v[202:203], v[138:139], v[202:203]
	v_pk_fma_f32 v[202:203], v[140:141], v[204:205], v[202:203]
	v_add_f32_dpp v146, v146, v146 quad_perm:[2,3,0,1] row_mask:0xf bank_mask:0xf bound_ctrl:1
	s_waitcnt lgkmcnt(5)
	v_pk_mul_f32 v[220:221], v[220:221], v[228:229] op_sel_hi:[1,0]
	v_add_f32_dpp v146, v146, v146 row_half_mirror row_mask:0xf bank_mask:0xf bound_ctrl:1
	v_pk_mul_f32 v[222:223], v[222:223], v[228:229] op_sel_hi:[1,0]
	v_add_f32 v161, v202, v203
	v_add_f32_dpp v146, v146, v146 row_mirror row_mask:0xf bank_mask:0xf bound_ctrl:1
	v_pk_fma_f32 v[220:221], v[146:147], v[212:213], v[220:221] op_sel_hi:[0,1,1] neg_lo:[1,0,0] neg_hi:[1,0,0]
	v_pk_fma_f32 v[222:223], v[146:147], v[214:215], v[222:223] op_sel_hi:[0,1,1] neg_lo:[1,0,0] neg_hi:[1,0,0]
	v_pk_fma_f32 v[138:139], v[138:139], v[216:217], v[220:221]
	v_pk_fma_f32 v[140:141], v[140:141], v[218:219], v[222:223]
	v_pk_mul_f32 v[144:145], v[138:139], v[230:231]
	v_pk_fma_f32 v[144:145], v[140:141], v[232:233], v[144:145]
	v_add_f32 v146, v144, v145
	s_nop 1
	v_add_f32_dpp v146, v146, v146 quad_perm:[1,0,3,2] row_mask:0xf bank_mask:0xf bound_ctrl:1
	v_pk_mul_f32 v[224:225], v[138:139], v[224:225]
	v_pk_fma_f32 v[224:225], v[140:141], v[226:227], v[224:225]
	v_add_f32_dpp v146, v146, v146 quad_perm:[2,3,0,1] row_mask:0xf bank_mask:0xf bound_ctrl:1
	s_waitcnt lgkmcnt(0)
	v_pk_mul_f32 v[242:243], v[242:243], v[250:251] op_sel_hi:[1,0]
	v_add_f32_dpp v146, v146, v146 row_half_mirror row_mask:0xf bank_mask:0xf bound_ctrl:1
	v_pk_mul_f32 v[244:245], v[244:245], v[250:251] op_sel_hi:[1,0]
	v_add_f32 v162, v224, v225
	v_add_f32_dpp v146, v146, v146 row_mirror row_mask:0xf bank_mask:0xf bound_ctrl:1
	v_pk_fma_f32 v[242:243], v[146:147], v[234:235], v[242:243] op_sel_hi:[0,1,1] neg_lo:[1,0,0] neg_hi:[1,0,0]
	v_pk_fma_f32 v[244:245], v[146:147], v[236:237], v[244:245] op_sel_hi:[0,1,1] neg_lo:[1,0,0] neg_hi:[1,0,0]
	v_pk_fma_f32 v[138:139], v[138:139], v[238:239], v[242:243]
	v_pk_fma_f32 v[140:141], v[140:141], v[240:241], v[244:245]
	v_pk_mul_f32 v[246:247], v[138:139], v[246:247]
	v_pk_fma_f32 v[246:247], v[140:141], v[248:249], v[246:247]
	v_add_f32 v163, v246, v247
	s_nop 0
	v_add_f32_dpp v102, v148, v148 row_mirror row_mask:0xf bank_mask:0x3 bound_ctrl:1
	v_add_f32_dpp v102, v156, v156 row_mirror row_mask:0xf bank_mask:0xc bound_ctrl:1
	v_add_f32_dpp v103, v149, v149 row_mirror row_mask:0xf bank_mask:0x3 bound_ctrl:1
	v_add_f32_dpp v103, v157, v157 row_mirror row_mask:0xf bank_mask:0xc bound_ctrl:1
	v_add_f32_dpp v104, v150, v150 row_mirror row_mask:0xf bank_mask:0x3 bound_ctrl:1
	v_add_f32_dpp v104, v158, v158 row_mirror row_mask:0xf bank_mask:0xc bound_ctrl:1
	v_add_f32_dpp v105, v151, v151 row_mirror row_mask:0xf bank_mask:0x3 bound_ctrl:1
	v_add_f32_dpp v105, v159, v159 row_mirror row_mask:0xf bank_mask:0xc bound_ctrl:1
	v_add_f32_dpp v106, v152, v152 row_mirror row_mask:0xf bank_mask:0x3 bound_ctrl:1
	v_add_f32_dpp v106, v160, v160 row_mirror row_mask:0xf bank_mask:0xc bound_ctrl:1
	v_add_f32_dpp v107, v153, v153 row_mirror row_mask:0xf bank_mask:0x3 bound_ctrl:1
	v_add_f32_dpp v107, v161, v161 row_mirror row_mask:0xf bank_mask:0xc bound_ctrl:1
	v_add_f32_dpp v108, v154, v154 row_mirror row_mask:0xf bank_mask:0x3 bound_ctrl:1
	v_add_f32_dpp v108, v162, v162 row_mirror row_mask:0xf bank_mask:0xc bound_ctrl:1
	v_add_f32_dpp v109, v155, v155 row_mirror row_mask:0xf bank_mask:0x3 bound_ctrl:1
	v_add_f32_dpp v109, v163, v163 row_mirror row_mask:0xf bank_mask:0xc bound_ctrl:1
	v_add_f32_dpp v110, v102, v102 row_half_mirror row_mask:0xf bank_mask:0x5 bound_ctrl:1
	v_add_f32_dpp v110, v106, v106 row_half_mirror row_mask:0xf bank_mask:0xa bound_ctrl:1
	v_add_f32_dpp v111, v103, v103 row_half_mirror row_mask:0xf bank_mask:0x5 bound_ctrl:1
	v_add_f32_dpp v111, v107, v107 row_half_mirror row_mask:0xf bank_mask:0xa bound_ctrl:1
	v_add_f32_dpp v112, v104, v104 row_half_mirror row_mask:0xf bank_mask:0x5 bound_ctrl:1
	v_add_f32_dpp v112, v108, v108 row_half_mirror row_mask:0xf bank_mask:0xa bound_ctrl:1
	v_add_f32_dpp v113, v105, v105 row_half_mirror row_mask:0xf bank_mask:0x5 bound_ctrl:1
	v_add_f32_dpp v113, v109, v109 row_half_mirror row_mask:0xf bank_mask:0xa bound_ctrl:1
	s_mov_b32 vcc_lo, 0xcccccccc
	s_mov_b32 vcc_hi, 0xcccccccc
	v_cndmask_b32 v116, v112, v110, vcc
	v_cndmask_b32 v117, v113, v111, vcc
	v_cndmask_b32 v114, v110, v112, vcc
	v_cndmask_b32 v115, v111, v113, vcc
	v_add_f32_dpp v114, v116, v114 quad_perm:[2,3,0,1] row_mask:0xf bank_mask:0xf bound_ctrl:1
	v_add_f32_dpp v115, v117, v115 quad_perm:[2,3,0,1] row_mask:0xf bank_mask:0xf bound_ctrl:1
	s_mov_b32 vcc_lo, 0xaaaaaaaa
	s_mov_b32 vcc_hi, 0xaaaaaaaa
	v_cndmask_b32 v116, v115, v114, vcc
	v_cndmask_b32 v117, v114, v115, vcc
	s_nop 0
	v_add_f32_dpp v19, v116, v117 quad_perm:[1,0,3,2] row_mask:0xf bank_mask:0xf bound_ctrl:1

; #define SCAN_BAR() asm volatile("s_barrier" ::: "memory")
; __device__ __forceinline__ void scan_unit(const Ctx& C0, const float* scn, int T, int quarter, const float* S0, float* Sout, unsigned char* obase, int mode) {
;     ...
;             if (mode == 0) { *(float*)(obase + (size_t)(k * 32 + q) * UPITCH_B + rl * 4) = osel0; *(float*)(obase + (size_t)(k * 32 + 16 + q) * UPITCH_B + rl * 4) = osel1; }
;             SCAN_BAR();
;         }
;         if (mode == 0) *(f32x4*)(Sout + irow * 64 + 4 * q) = (f32x4){S0x, S1x, S2x, S3x};
	global_store_dword v6, v18, s[98:99]
	s_add_u32 s98, s98, 0x2b000
	s_addc_u32 s99, s99, 0
	global_store_dword v6, v19, s[98:99]
	s_add_u32 s98, s98, 0x2b000
	s_addc_u32 s99, s99, 0
	s_add_u32 s0, s0, 0xac000
	s_addc_u32 s1, s1, 0
	s_cmp_lg_u32 s0, 0x5600000
	s_barrier
	s_cbranch_scc1 .LBB0_685
	v_mov_b32_e32 v2, v138
	v_mov_b32_e32 v13, v139
	v_mov_b32_e32 v12, v140
	v_mov_b32_e32 v8, v141
	v_readlane_b32 s0, v255, 46
	s_add_i32 s0, s3, s0
	s_ashr_i32 s1, s0, 31
	s_lshl_b64 s[0:1], s[0:1], 17
	v_readlane_b32 s3, v253, 26
	s_add_u32 s0, s3, s0
	v_readlane_b32 s3, v253, 27
	s_addc_u32 s1, s3, s1
	s_lshl_b32 s2, s2, 14
	s_add_u32 s0, s0, s2
	s_addc_u32 s1, s1, 0
	v_lshlrev_b32_e32 v0, 8, v0
	v_lshl_add_u64 v[6:7], s[0:1], 0, v[0:1]
	v_mov_b32_e32 v5, v1
	v_lshl_add_u64 v[6:7], v[6:7], 0, v[4:5]
	v_mov_b32_e32 v3, v13
	v_mov_b32_e32 v4, v12
	v_mov_b32_e32 v5, v8
	global_store_dwordx4 v[6:7], v[2:5], off
